# v33 + GATE epilogue: duplicated 64-bit o-tile address chain (2 v_mad_u64_u32 + 4 VALU per block) replaced by one v_mov_b64 from the hoisted address
# speedup vs baseline: 1.0106x; 1.0106x over previous
; DI unsigned pk(float lo, float hi) { f32x2 v = {lo, hi}; bf2_t b = __builtin_convertvector(v, bf2_t); return __builtin_bit_cast(unsigned, b); }
; DI float bflo(unsigned w) { return __uint_as_float(w << 16); }
; DI float bfhi(unsigned w) { return __uint_as_float(w & 0xffff0000u); }
; DI float sigmoidf_(float x) { return 1.0f / (1.0f + __expf(-x)); }
; DI void gemm_epilogue(const GemmDesc& g, f32x4 (&acc)[2][2][4][2], int brow, int bcol, int wr, int wc, int fr, int fq) {
;     ...
;           const int row = rowb + ai * HALF + m * 16;
;           float rs;
;           { const float* sp = g.f0 + (size_t)row * 32 + head * 8;
;             const f32x4 s0 = gld<f32x4>(sp); float ssum = (s0[0] + s0[1]) + (s0[2] + s0[3]);
;             if (g.dvshift == 9) { const f32x4 s1 = gld<f32x4>(sp + 4); ssum += (s1[0] + s1[1]) + (s1[2] + s1[3]); }
;             rs = rsqrtf(ssum * (g.dvshift == 9 ? (1.0f / 512.0f) : (1.0f / 256.0f)) + EPS); }
;           bf16_t* op = g.o0 + (size_t)row * N + col;
;           const u32x4 ow = gld<u32x4>(op);
;           const float ru = gld<float>(g.rowscale + row);
;           const f32x4 v0 = acc[ai][bj][m][0] * ru, v1 = acc[ai][bj][m][1] * ru;
;           float o[8] = {bflo(ow.x), bfhi(ow.x), bflo(ow.y), bfhi(ow.y), bflo(ow.z), bfhi(ow.z), bflo(ow.w), bfhi(ow.w)};
; #pragma unroll
;           for (int j = 0; j < 4; ++j) { o[j] = o[j] * rs * g0[j] * v0[j] * sigmoidf_(v0[j]); o[4 + j] = o[4 + j] * rs * g1[j] * v1[j] * sigmoidf_(v1[j]); }
;           u32x4 w; w.x = pk(o[0], o[1]); w.y = pk(o[2], o[3]); w.z = pk(o[4], o[5]); w.w = pk(o[6], o[7]);
;           gst<u32x4>(op, w);
.LBB0_223:
	v_fma_f32 v138, s26, v138, v204
	v_cmp_gt_f32_e32 vcc, s33, v138
	v_mul_f32_e32 v139, 0x4b800000, v138
	s_nop 0
	v_cndmask_b32_e32 v138, v138, v139, vcc
	v_rsq_f32_e32 v138, v138
	s_nop 0
	v_mul_f32_e32 v139, 0x45800000, v138
	v_cndmask_b32_e32 v148, v138, v139, vcc
	v_mov_b64_e32 v[168:169], v[236:237]
	v_mov_b64_e32 v[136:137], v[242:243]
	v_mov_b64_e32 v[138:139], v[244:245]
	v_mov_b32_e32 v170, v246
	v_lshlrev_b32_e32 v172, 16, v136
	v_pk_mul_f32 v[174:175], v[116:117], v[170:171] op_sel_hi:[1,0]
	v_and_b32_e32 v173, 0xffff0000, v136
	v_mul_f32_e32 v136, 0xbfb8aa3b, v174
	v_exp_f32_e32 v176, v136
	v_mul_f32_e32 v136, 0xbfb8aa3b, v175
	v_exp_f32_e32 v177, v136
	v_pk_mul_f32 v[172:173], v[148:149], v[172:173] op_sel_hi:[0,1]
	v_pk_mul_f32 v[172:173], v[132:133], v[172:173]
	s_nop 0
	v_pk_mul_f32 v[172:173], v[174:175], v[172:173]
	v_pk_add_f32 v[174:175], v[176:177], 1.0 op_sel_hi:[1,0]
	s_nop 0
	v_div_scale_f32 v136, s[26:27], v175, v175, 1.0
	v_rcp_f32_e32 v167, v136
	s_nop 0
	v_fma_f32 v171, -v136, v167, 1.0
	v_fmac_f32_e32 v167, v171, v167
	v_div_scale_f32 v171, vcc, 1.0, v175, 1.0
	v_mul_f32_e32 v176, v171, v167
	v_fma_f32 v177, -v136, v176, v171
	v_fmac_f32_e32 v176, v177, v167
	v_fma_f32 v136, -v136, v176, v171
	v_div_fmas_f32 v136, v136, v167, v176
	v_div_fixup_f32 v175, v136, v175, 1.0
	v_div_scale_f32 v136, s[26:27], v174, v174, 1.0
	v_rcp_f32_e32 v167, v136
	s_nop 0
	v_fma_f32 v171, -v136, v167, 1.0
	v_fmac_f32_e32 v167, v171, v167
	v_div_scale_f32 v171, vcc, 1.0, v174, 1.0
	v_mul_f32_e32 v176, v171, v167
	v_fma_f32 v177, -v136, v176, v171
	v_fmac_f32_e32 v176, v177, v167
	v_fma_f32 v136, -v136, v176, v171
	v_div_fmas_f32 v136, v136, v167, v176
	v_pk_mul_f32 v[176:177], v[112:113], v[170:171] op_sel_hi:[1,0]
	v_div_fixup_f32 v174, v136, v174, 1.0
	v_mul_f32_e32 v136, 0xbfb8aa3b, v176
	v_exp_f32_e32 v178, v136
	v_mul_f32_e32 v136, 0xbfb8aa3b, v177
	v_exp_f32_e32 v179, v136
	v_pk_mul_f32 v[172:173], v[174:175], v[172:173]
	v_lshlrev_b32_e32 v174, 16, v138
	v_and_b32_e32 v175, 0xffff0000, v138
	v_pk_mul_f32 v[174:175], v[148:149], v[174:175] op_sel_hi:[0,1]
	v_pk_mul_f32 v[174:175], v[128:129], v[174:175]
	s_nop 0
	v_pk_mul_f32 v[174:175], v[176:177], v[174:175]
	v_pk_add_f32 v[176:177], v[178:179], 1.0 op_sel_hi:[1,0]
	s_nop 0
	v_div_scale_f32 v136, s[26:27], v177, v177, 1.0
	v_rcp_f32_e32 v138, v136
	s_nop 0
	v_fma_f32 v167, -v136, v138, 1.0
	v_fmac_f32_e32 v138, v167, v138
	v_div_scale_f32 v167, vcc, 1.0, v177, 1.0
	v_mul_f32_e32 v171, v167, v138
	v_fma_f32 v178, -v136, v171, v167
	v_fmac_f32_e32 v171, v178, v138
	v_fma_f32 v136, -v136, v171, v167
	v_div_fmas_f32 v136, v136, v138, v171
	v_div_fixup_f32 v177, v136, v177, 1.0
	v_div_scale_f32 v136, s[26:27], v176, v176, 1.0
	v_rcp_f32_e32 v138, v136
	s_nop 0
	v_fma_f32 v167, -v136, v138, 1.0
	v_fmac_f32_e32 v138, v167, v138
	v_div_scale_f32 v167, vcc, 1.0, v176, 1.0
	v_mul_f32_e32 v171, v167, v138
	v_fma_f32 v178, -v136, v171, v167
	v_fmac_f32_e32 v171, v178, v138
	v_fma_f32 v136, -v136, v171, v167
	v_div_fmas_f32 v136, v136, v138, v171
	v_pk_mul_f32 v[178:179], v[118:119], v[170:171] op_sel_hi:[1,0]
	v_div_fixup_f32 v176, v136, v176, 1.0
	v_mul_f32_e32 v138, 0xbfb8aa3b, v178
	v_pk_mul_f32 v[174:175], v[176:177], v[174:175]
	v_exp_f32_e32 v176, v138
	v_mul_f32_e32 v138, 0xbfb8aa3b, v179
	v_exp_f32_e32 v177, v138
	v_lshlrev_b32_e32 v136, 16, v137
	v_and_b32_e32 v137, 0xffff0000, v137
	v_pk_mul_f32 v[136:137], v[148:149], v[136:137] op_sel_hi:[0,1]
	v_pk_add_f32 v[176:177], v[176:177], 1.0 op_sel_hi:[1,0]
	v_pk_mul_f32 v[136:137], v[134:135], v[136:137]
	v_div_scale_f32 v138, s[26:27], v177, v177, 1.0
	v_rcp_f32_e32 v167, v138
	v_pk_mul_f32 v[136:137], v[178:179], v[136:137]
	v_fma_f32 v171, -v138, v167, 1.0
	v_fmac_f32_e32 v167, v171, v167
	v_div_scale_f32 v171, vcc, 1.0, v177, 1.0
	v_mul_f32_e32 v178, v171, v167
	v_fma_f32 v179, -v138, v178, v171
	v_fmac_f32_e32 v178, v179, v167
	v_fma_f32 v138, -v138, v178, v171
	v_div_fmas_f32 v138, v138, v167, v178
	v_div_fixup_f32 v177, v138, v177, 1.0
	v_div_scale_f32 v138, s[26:27], v176, v176, 1.0
	v_rcp_f32_e32 v167, v138
	s_nop 0
	v_fma_f32 v171, -v138, v167, 1.0
	v_fmac_f32_e32 v167, v171, v167
	v_div_scale_f32 v171, vcc, 1.0, v176, 1.0
	v_mul_f32_e32 v178, v171, v167
	v_fma_f32 v179, -v138, v178, v171
	v_fmac_f32_e32 v178, v179, v167
	v_fma_f32 v138, -v138, v178, v171
	v_div_fmas_f32 v138, v138, v167, v178
	v_div_fixup_f32 v176, v138, v176, 1.0
	v_pk_mul_f32 v[176:177], v[176:177], v[136:137]
	v_lshlrev_b32_e32 v136, 16, v139
	v_and_b32_e32 v137, 0xffff0000, v139
	v_pk_mul_f32 v[136:137], v[148:149], v[136:137] op_sel_hi:[0,1]
	v_pk_mul_f32 v[138:139], v[114:115], v[170:171] op_sel_hi:[1,0]
	v_pk_mul_f32 v[136:137], v[130:131], v[136:137]
	v_mul_f32_e32 v167, 0xbfb8aa3b, v138
	v_pk_mul_f32 v[136:137], v[138:139], v[136:137]
	v_mul_f32_e32 v138, 0xbfb8aa3b, v139
	v_exp_f32_e32 v170, v167
	v_exp_f32_e32 v171, v138
	s_nop 0
	v_pk_add_f32 v[138:139], v[170:171], 1.0 op_sel_hi:[1,0]
	s_nop 0
	v_div_scale_f32 v148, s[26:27], v139, v139, 1.0
	v_rcp_f32_e32 v167, v148
	s_nop 0
	v_fma_f32 v170, -v148, v167, 1.0
	v_fmac_f32_e32 v167, v170, v167
	v_div_scale_f32 v170, vcc, 1.0, v139, 1.0
	v_mul_f32_e32 v171, v170, v167
	v_fma_f32 v178, -v148, v171, v170
	v_fmac_f32_e32 v171, v178, v167
	v_fma_f32 v148, -v148, v171, v170
	v_div_fmas_f32 v148, v148, v167, v171
	v_div_fixup_f32 v139, v148, v139, 1.0
	v_div_scale_f32 v148, s[26:27], v138, v138, 1.0
	v_rcp_f32_e32 v167, v148
	s_mov_b32 s26, 0x3b800000
	s_mov_b32 s27, 0x3b800000
	v_fma_f32 v170, -v148, v167, 1.0
	v_fmac_f32_e32 v167, v170, v167
	v_div_scale_f32 v170, vcc, 1.0, v138, 1.0
	v_mul_f32_e32 v171, v170, v167
	v_fma_f32 v178, -v148, v171, v170
	v_fmac_f32_e32 v171, v178, v167
	v_fma_f32 v148, -v148, v171, v170
	v_div_fmas_f32 v148, v148, v167, v171
	v_div_fixup_f32 v138, v148, v138, 1.0
	v_pk_mul_f32 v[170:171], v[138:139], v[136:137]
	v_cvt_pk_bf16_f32 v136, v172, v173
	v_cvt_pk_bf16_f32 v137, v176, v177
	v_cvt_pk_bf16_f32 v138, v174, v175
	v_cvt_pk_bf16_f32 v139, v170, v171
	global_store_dwordx4 v[168:169], v[136:139], off
	s_and_b64 vcc, exec, s[44:45]
	s_nop 0
	v_or_b32_e32 v136, 32, v166
	v_ashrrev_i32_e32 v137, 31, v136
	v_lshlrev_b64 v[138:139], 7, v[136:137]
	v_lshl_add_u64 v[186:187], s[66:67], 0, v[138:139]
	v_lshl_add_u64 v[170:171], v[180:181], 2, v[186:187]
	global_load_dwordx4 v[172:175], v[170:171], off
	global_load_dwordx4 v[232:235], v[170:171], off offset:16
	v_mad_u64_u32 v[238:239], s[100:101], v136, s70, 0
	v_mov_b32_e32 v240, v239
	v_mad_u64_u32 v[240:241], s[100:101], v137, s70, v[240:241]
	v_mov_b32_e32 v239, v240
	v_lshl_add_u64 v[238:239], v[238:239], 1, s[64:65]
	v_lshl_add_u64 v[236:237], v[164:165], 1, v[238:239]
	global_load_dwordx4 v[242:245], v[236:237], off
	global_load_dword v246, v[140:141], off offset:128
	s_waitcnt vmcnt(0)
; DI unsigned pk(float lo, float hi) { f32x2 v = {lo, hi}; bf2_t b = __builtin_convertvector(v, bf2_t); return __builtin_bit_cast(unsigned, b); }
; DI float bflo(unsigned w) { return __uint_as_float(w << 16); }
; DI float bfhi(unsigned w) { return __uint_as_float(w & 0xffff0000u); }
; DI float sigmoidf_(float x) { return 1.0f / (1.0f + __expf(-x)); }
; DI void gemm_epilogue(const GemmDesc& g, f32x4 (&acc)[2][2][4][2], int brow, int bcol, int wr, int wc, int fr, int fq) {
;     ...
;           const int row = rowb + ai * HALF + m * 16;
;           float rs;
;           { const float* sp = g.f0 + (size_t)row * 32 + head * 8;
;             const f32x4 s0 = gld<f32x4>(sp); float ssum = (s0[0] + s0[1]) + (s0[2] + s0[3]);
;             if (g.dvshift == 9) { const f32x4 s1 = gld<f32x4>(sp + 4); ssum += (s1[0] + s1[1]) + (s1[2] + s1[3]); }
;             rs = rsqrtf(ssum * (g.dvshift == 9 ? (1.0f / 512.0f) : (1.0f / 256.0f)) + EPS); }
;           bf16_t* op = g.o0 + (size_t)row * N + col;
;           const u32x4 ow = gld<u32x4>(op);
;           const float ru = gld<float>(g.rowscale + row);
;           const f32x4 v0 = acc[ai][bj][m][0] * ru, v1 = acc[ai][bj][m][1] * ru;
;           float o[8] = {bflo(ow.x), bfhi(ow.x), bflo(ow.y), bfhi(ow.y), bflo(ow.z), bfhi(ow.z), bflo(ow.w), bfhi(ow.w)};
; #pragma unroll
;           for (int j = 0; j < 4; ++j) { o[j] = o[j] * rs * g0[j] * v0[j] * sigmoidf_(v0[j]); o[4 + j] = o[4 + j] * rs * g1[j] * v1[j] * sigmoidf_(v1[j]); }
;           u32x4 w; w.x = pk(o[0], o[1]); w.y = pk(o[2], o[3]); w.z = pk(o[4], o[5]); w.w = pk(o[6], o[7]);
;           gst<u32x4>(op, w);
	v_mov_b32_e32 v138, v173
	v_mov_b32_e32 v139, v174
	v_mov_b32_e32 v173, v175
	v_pk_add_f32 v[138:139], v[138:139], v[172:173]
	s_nop 0
	v_pk_add_f32 v[138:139], v[138:139], v[138:139] op_sel:[0,1] op_sel_hi:[1,0]
	s_cbranch_vccnz .LBB0_225
	v_mov_b64_e32 v[170:171], v[232:233]
	v_mov_b64_e32 v[172:173], v[234:235]
	s_mov_b32 s27, 0x3b000000
	v_mov_b32_e32 v174, v171
	v_mov_b32_e32 v175, v172
	v_mov_b32_e32 v171, v173
	v_pk_add_f32 v[170:171], v[174:175], v[170:171]
	s_nop 0
	v_add_f32_e32 v139, v170, v171
	v_add_f32_e32 v138, v138, v139
.LBB0_225:
	v_fma_f32 v138, s27, v138, v204
	v_cmp_gt_f32_e32 vcc, s33, v138
	v_mul_f32_e32 v139, 0x4b800000, v138
	s_nop 0
	v_cndmask_b32_e32 v138, v138, v139, vcc
	v_rsq_f32_e32 v138, v138
	s_nop 0
	v_mul_f32_e32 v139, 0x45800000, v138
	v_cndmask_b32_e32 v148, v138, v139, vcc
	v_mov_b64_e32 v[170:171], v[236:237]
	v_mov_b64_e32 v[136:137], v[242:243]
	v_mov_b64_e32 v[138:139], v[244:245]
	v_mov_b32_e32 v172, v246
	v_lshlrev_b32_e32 v174, 16, v136
	v_pk_mul_f32 v[176:177], v[108:109], v[172:173] op_sel_hi:[1,0]
	v_and_b32_e32 v175, 0xffff0000, v136
	v_mul_f32_e32 v136, 0xbfb8aa3b, v176
	v_exp_f32_e32 v178, v136
	v_mul_f32_e32 v136, 0xbfb8aa3b, v177
	v_exp_f32_e32 v179, v136
	v_pk_mul_f32 v[174:175], v[148:149], v[174:175] op_sel_hi:[0,1]
	v_pk_mul_f32 v[174:175], v[132:133], v[174:175]
	s_nop 0
	v_pk_mul_f32 v[174:175], v[176:177], v[174:175]
	v_pk_add_f32 v[176:177], v[178:179], 1.0 op_sel_hi:[1,0]
	s_nop 0
	v_div_scale_f32 v136, vcc, v177, v177, 1.0
	v_rcp_f32_e32 v167, v136
	s_nop 0
	v_fma_f32 v173, -v136, v167, 1.0
	v_fmac_f32_e32 v167, v173, v167
	v_div_scale_f32 v173, vcc, 1.0, v177, 1.0
	v_mul_f32_e32 v178, v173, v167
	v_fma_f32 v179, -v136, v178, v173
	v_fmac_f32_e32 v178, v179, v167
	v_fma_f32 v136, -v136, v178, v173
	v_div_fmas_f32 v136, v136, v167, v178
	v_div_fixup_f32 v177, v136, v177, 1.0
	v_div_scale_f32 v136, vcc, v176, v176, 1.0
	v_rcp_f32_e32 v167, v136
	s_nop 0
	v_fma_f32 v173, -v136, v167, 1.0
	v_fmac_f32_e32 v167, v173, v167
	v_div_scale_f32 v173, vcc, 1.0, v176, 1.0
	v_mul_f32_e32 v178, v173, v167
	v_fma_f32 v179, -v136, v178, v173
	v_fmac_f32_e32 v178, v179, v167
	v_fma_f32 v136, -v136, v178, v173
	v_div_fmas_f32 v136, v136, v167, v178
	v_pk_mul_f32 v[178:179], v[104:105], v[172:173] op_sel_hi:[1,0]
	v_div_fixup_f32 v176, v136, v176, 1.0
	v_mul_f32_e32 v136, 0xbfb8aa3b, v178
	v_exp_f32_e32 v188, v136
	v_mul_f32_e32 v136, 0xbfb8aa3b, v179
	v_exp_f32_e32 v189, v136
	v_pk_mul_f32 v[174:175], v[176:177], v[174:175]
	v_lshlrev_b32_e32 v176, 16, v138
	v_and_b32_e32 v177, 0xffff0000, v138
	v_pk_mul_f32 v[176:177], v[148:149], v[176:177] op_sel_hi:[0,1]
	v_pk_mul_f32 v[176:177], v[128:129], v[176:177]
	s_nop 0
	v_pk_mul_f32 v[176:177], v[178:179], v[176:177]
	v_pk_add_f32 v[178:179], v[188:189], 1.0 op_sel_hi:[1,0]
	s_nop 0
	v_div_scale_f32 v136, vcc, v179, v179, 1.0
	v_rcp_f32_e32 v138, v136
	s_nop 0
	v_fma_f32 v167, -v136, v138, 1.0
	v_fmac_f32_e32 v138, v167, v138
	v_div_scale_f32 v167, vcc, 1.0, v179, 1.0
	v_mul_f32_e32 v173, v167, v138
	v_fma_f32 v188, -v136, v173, v167
	v_fmac_f32_e32 v173, v188, v138
	v_fma_f32 v136, -v136, v173, v167
	v_div_fmas_f32 v136, v136, v138, v173
	v_div_fixup_f32 v179, v136, v179, 1.0
	v_div_scale_f32 v136, vcc, v178, v178, 1.0
	v_rcp_f32_e32 v138, v136
	s_nop 0
	v_fma_f32 v167, -v136, v138, 1.0
	v_fmac_f32_e32 v138, v167, v138
	v_div_scale_f32 v167, vcc, 1.0, v178, 1.0
	v_mul_f32_e32 v173, v167, v138
	v_fma_f32 v188, -v136, v173, v167
	v_fmac_f32_e32 v173, v188, v138
	v_fma_f32 v136, -v136, v173, v167
	v_div_fmas_f32 v136, v136, v138, v173
	v_pk_mul_f32 v[188:189], v[110:111], v[172:173] op_sel_hi:[1,0]
	v_div_fixup_f32 v178, v136, v178, 1.0
	v_mul_f32_e32 v138, 0xbfb8aa3b, v188
	v_pk_mul_f32 v[176:177], v[178:179], v[176:177]
	v_exp_f32_e32 v178, v138
	v_mul_f32_e32 v138, 0xbfb8aa3b, v189
	v_exp_f32_e32 v179, v138
	v_lshlrev_b32_e32 v136, 16, v137
	v_and_b32_e32 v137, 0xffff0000, v137
	v_pk_mul_f32 v[136:137], v[148:149], v[136:137] op_sel_hi:[0,1]
	v_pk_add_f32 v[178:179], v[178:179], 1.0 op_sel_hi:[1,0]
	v_pk_mul_f32 v[136:137], v[134:135], v[136:137]
	v_div_scale_f32 v138, vcc, v179, v179, 1.0
	v_rcp_f32_e32 v167, v138
	v_pk_mul_f32 v[136:137], v[188:189], v[136:137]
	v_fma_f32 v173, -v138, v167, 1.0
	v_fmac_f32_e32 v167, v173, v167
	v_div_scale_f32 v173, vcc, 1.0, v179, 1.0
	v_mul_f32_e32 v188, v173, v167
	v_fma_f32 v189, -v138, v188, v173
	v_fmac_f32_e32 v188, v189, v167
	v_fma_f32 v138, -v138, v188, v173
	v_div_fmas_f32 v138, v138, v167, v188
	v_div_fixup_f32 v179, v138, v179, 1.0
	v_div_scale_f32 v138, vcc, v178, v178, 1.0
	v_rcp_f32_e32 v167, v138
	s_nop 0
	v_fma_f32 v173, -v138, v167, 1.0
	v_fmac_f32_e32 v167, v173, v167
	v_div_scale_f32 v173, vcc, 1.0, v178, 1.0
	v_mul_f32_e32 v188, v173, v167
	v_fma_f32 v189, -v138, v188, v173
	v_fmac_f32_e32 v188, v189, v167
	v_fma_f32 v138, -v138, v188, v173
	v_div_fmas_f32 v138, v138, v167, v188
	v_div_fixup_f32 v178, v138, v178, 1.0
	v_pk_mul_f32 v[178:179], v[178:179], v[136:137]
	v_lshlrev_b32_e32 v136, 16, v139
	v_and_b32_e32 v137, 0xffff0000, v139
	v_pk_mul_f32 v[136:137], v[148:149], v[136:137] op_sel_hi:[0,1]
	v_pk_mul_f32 v[138:139], v[106:107], v[172:173] op_sel_hi:[1,0]
	v_pk_mul_f32 v[136:137], v[130:131], v[136:137]
	v_mul_f32_e32 v167, 0xbfb8aa3b, v138
	v_pk_mul_f32 v[136:137], v[138:139], v[136:137]
	v_mul_f32_e32 v138, 0xbfb8aa3b, v139
	v_exp_f32_e32 v172, v167
	v_exp_f32_e32 v173, v138
	s_nop 0
	v_pk_add_f32 v[138:139], v[172:173], 1.0 op_sel_hi:[1,0]
	s_nop 0
	v_div_scale_f32 v148, vcc, v139, v139, 1.0
	v_rcp_f32_e32 v167, v148
	s_nop 0
	v_fma_f32 v172, -v148, v167, 1.0
; DI unsigned pk(float lo, float hi) { f32x2 v = {lo, hi}; bf2_t b = __builtin_convertvector(v, bf2_t); return __builtin_bit_cast(unsigned, b); }
; DI float bflo(unsigned w) { return __uint_as_float(w << 16); }
; DI float bfhi(unsigned w) { return __uint_as_float(w & 0xffff0000u); }
; DI float sigmoidf_(float x) { return 1.0f / (1.0f + __expf(-x)); }
; DI void gemm_epilogue(const GemmDesc& g, f32x4 (&acc)[2][2][4][2], int brow, int bcol, int wr, int wc, int fr, int fq) {
;     ...
;           const int row = rowb + ai * HALF + m * 16;
;           float rs;
;           { const float* sp = g.f0 + (size_t)row * 32 + head * 8;
;             const f32x4 s0 = gld<f32x4>(sp); float ssum = (s0[0] + s0[1]) + (s0[2] + s0[3]);
;             if (g.dvshift == 9) { const f32x4 s1 = gld<f32x4>(sp + 4); ssum += (s1[0] + s1[1]) + (s1[2] + s1[3]); }
;             rs = rsqrtf(ssum * (g.dvshift == 9 ? (1.0f / 512.0f) : (1.0f / 256.0f)) + EPS); }
;           bf16_t* op = g.o0 + (size_t)row * N + col;
;           const u32x4 ow = gld<u32x4>(op);
;           const float ru = gld<float>(g.rowscale + row);
;           const f32x4 v0 = acc[ai][bj][m][0] * ru, v1 = acc[ai][bj][m][1] * ru;
;           float o[8] = {bflo(ow.x), bfhi(ow.x), bflo(ow.y), bfhi(ow.y), bflo(ow.z), bfhi(ow.z), bflo(ow.w), bfhi(ow.w)};
; #pragma unroll
;           for (int j = 0; j < 4; ++j) { o[j] = o[j] * rs * g0[j] * v0[j] * sigmoidf_(v0[j]); o[4 + j] = o[4 + j] * rs * g1[j] * v1[j] * sigmoidf_(v1[j]); }
;           u32x4 w; w.x = pk(o[0], o[1]); w.y = pk(o[2], o[3]); w.z = pk(o[4], o[5]); w.w = pk(o[6], o[7]);
;           gst<u32x4>(op, w);
	v_fmac_f32_e32 v167, v172, v167
	v_div_scale_f32 v172, vcc, 1.0, v139, 1.0
	v_mul_f32_e32 v173, v172, v167
	v_fma_f32 v188, -v148, v173, v172
	v_fmac_f32_e32 v173, v188, v167
	v_fma_f32 v148, -v148, v173, v172
	v_div_fmas_f32 v148, v148, v167, v173
	v_div_fixup_f32 v139, v148, v139, 1.0
	v_div_scale_f32 v148, vcc, v138, v138, 1.0
	v_rcp_f32_e32 v167, v148
	s_nop 0
	v_fma_f32 v172, -v148, v167, 1.0
	v_fmac_f32_e32 v167, v172, v167
	v_div_scale_f32 v172, vcc, 1.0, v138, 1.0
	v_mul_f32_e32 v173, v172, v167
	v_fma_f32 v188, -v148, v173, v172
	v_fmac_f32_e32 v173, v188, v167
	v_fma_f32 v148, -v148, v173, v172
	v_div_fmas_f32 v148, v148, v167, v173
	v_div_fixup_f32 v138, v148, v138, 1.0
	v_pk_mul_f32 v[172:173], v[138:139], v[136:137]
	v_cvt_pk_bf16_f32 v136, v174, v175
	v_cvt_pk_bf16_f32 v137, v178, v179
	v_cvt_pk_bf16_f32 v138, v176, v177
	v_cvt_pk_bf16_f32 v139, v172, v173
	global_store_dwordx4 v[170:171], v[136:139], off
	s_and_b64 vcc, exec, s[44:45]
	s_nop 0
	v_or_b32_e32 v136, 48, v166
	v_ashrrev_i32_e32 v137, 31, v136
	v_lshlrev_b64 v[138:139], 7, v[136:137]
	v_lshl_add_u64 v[188:189], s[66:67], 0, v[138:139]
	v_lshl_add_u64 v[172:173], v[180:181], 2, v[188:189]
	global_load_dwordx4 v[174:177], v[172:173], off
	global_load_dwordx4 v[232:235], v[172:173], off offset:16
	v_mad_u64_u32 v[238:239], s[100:101], v136, s70, 0
	v_mov_b32_e32 v240, v239
	v_mad_u64_u32 v[240:241], s[100:101], v137, s70, v[240:241]
	v_mov_b32_e32 v239, v240
	v_lshl_add_u64 v[238:239], v[238:239], 1, s[64:65]
	v_lshl_add_u64 v[236:237], v[164:165], 1, v[238:239]
	global_load_dwordx4 v[242:245], v[236:237], off
	global_load_dword v246, v[140:141], off offset:192
	s_waitcnt vmcnt(0)
	v_mov_b32_e32 v138, v175
	v_mov_b32_e32 v139, v176
	v_mov_b32_e32 v175, v177
	v_pk_add_f32 v[138:139], v[138:139], v[174:175]
	s_nop 0
	v_pk_add_f32 v[138:139], v[138:139], v[138:139] op_sel:[0,1] op_sel_hi:[1,0]
	s_cbranch_vccnz .LBB0_227
	v_mov_b64_e32 v[172:173], v[232:233]
	v_mov_b64_e32 v[174:175], v[234:235]
	s_mov_b32 s26, 0x3b000000
	v_mov_b32_e32 v176, v173
	v_mov_b32_e32 v177, v174
	v_mov_b32_e32 v173, v175
	v_pk_add_f32 v[172:173], v[176:177], v[172:173]
	s_nop 0
	v_add_f32_e32 v139, v172, v173
	v_add_f32_e32 v138, v138, v139
.LBB0_227:
	v_fma_f32 v138, s26, v138, v204
	v_cmp_gt_f32_e32 vcc, s33, v138
	v_mul_f32_e32 v139, 0x4b800000, v138
	s_nop 0
	v_cndmask_b32_e32 v138, v138, v139, vcc
	v_rsq_f32_e32 v138, v138
	s_nop 0
	v_mul_f32_e32 v139, 0x45800000, v138
	v_cndmask_b32_e32 v148, v138, v139, vcc
	v_mov_b64_e32 v[172:173], v[236:237]
	v_mov_b64_e32 v[136:137], v[242:243]
	v_mov_b64_e32 v[138:139], v[244:245]
	v_mov_b32_e32 v174, v246
	v_lshlrev_b32_e32 v176, 16, v136
	v_pk_mul_f32 v[178:179], v[100:101], v[174:175] op_sel_hi:[1,0]
	v_and_b32_e32 v177, 0xffff0000, v136
	v_mul_f32_e32 v136, 0xbfb8aa3b, v178
	v_exp_f32_e32 v190, v136
	v_mul_f32_e32 v136, 0xbfb8aa3b, v179
	v_exp_f32_e32 v191, v136
	v_pk_mul_f32 v[176:177], v[148:149], v[176:177] op_sel_hi:[0,1]
	v_pk_mul_f32 v[176:177], v[132:133], v[176:177]
	s_nop 0
	v_pk_mul_f32 v[176:177], v[178:179], v[176:177]
	v_pk_add_f32 v[178:179], v[190:191], 1.0 op_sel_hi:[1,0]
	s_nop 0
	v_div_scale_f32 v136, s[26:27], v179, v179, 1.0
	v_rcp_f32_e32 v167, v136
	s_nop 0
	v_fma_f32 v175, -v136, v167, 1.0
	v_fmac_f32_e32 v167, v175, v167
	v_div_scale_f32 v175, vcc, 1.0, v179, 1.0
	v_mul_f32_e32 v190, v175, v167
	v_fma_f32 v191, -v136, v190, v175
	v_fmac_f32_e32 v190, v191, v167
	v_fma_f32 v136, -v136, v190, v175
	v_div_fmas_f32 v136, v136, v167, v190
	v_div_fixup_f32 v179, v136, v179, 1.0
	v_div_scale_f32 v136, s[26:27], v178, v178, 1.0
	v_rcp_f32_e32 v167, v136
	s_nop 0
	v_fma_f32 v175, -v136, v167, 1.0
	v_fmac_f32_e32 v167, v175, v167
	v_div_scale_f32 v175, vcc, 1.0, v178, 1.0
	v_mul_f32_e32 v190, v175, v167
	v_fma_f32 v191, -v136, v190, v175
	v_fmac_f32_e32 v190, v191, v167
	v_fma_f32 v136, -v136, v190, v175
	v_div_fmas_f32 v136, v136, v167, v190
	v_pk_mul_f32 v[190:191], v[96:97], v[174:175] op_sel_hi:[1,0]
	v_div_fixup_f32 v178, v136, v178, 1.0
	v_mul_f32_e32 v136, 0xbfb8aa3b, v190
	v_exp_f32_e32 v192, v136
	v_mul_f32_e32 v136, 0xbfb8aa3b, v191
	v_exp_f32_e32 v193, v136
	v_pk_mul_f32 v[176:177], v[178:179], v[176:177]
	v_lshlrev_b32_e32 v178, 16, v138
	v_and_b32_e32 v179, 0xffff0000, v138
	v_pk_mul_f32 v[178:179], v[148:149], v[178:179] op_sel_hi:[0,1]
	v_pk_mul_f32 v[178:179], v[128:129], v[178:179]
	s_nop 0
	v_pk_mul_f32 v[178:179], v[190:191], v[178:179]
	v_pk_add_f32 v[190:191], v[192:193], 1.0 op_sel_hi:[1,0]
	s_nop 0
	v_div_scale_f32 v136, s[26:27], v191, v191, 1.0
	v_rcp_f32_e32 v138, v136
	s_nop 0
	v_fma_f32 v167, -v136, v138, 1.0
	v_fmac_f32_e32 v138, v167, v138
	v_div_scale_f32 v167, vcc, 1.0, v191, 1.0
	v_mul_f32_e32 v175, v167, v138
	v_fma_f32 v192, -v136, v175, v167
	v_fmac_f32_e32 v175, v192, v138
	v_fma_f32 v136, -v136, v175, v167
	v_div_fmas_f32 v136, v136, v138, v175
	v_div_fixup_f32 v191, v136, v191, 1.0
	v_div_scale_f32 v136, s[26:27], v190, v190, 1.0
	v_rcp_f32_e32 v138, v136
	s_nop 0
	v_fma_f32 v167, -v136, v138, 1.0
	v_fmac_f32_e32 v138, v167, v138
	v_div_scale_f32 v167, vcc, 1.0, v190, 1.0
	v_mul_f32_e32 v175, v167, v138
	v_fma_f32 v192, -v136, v175, v167
	v_fmac_f32_e32 v175, v192, v138
	v_fma_f32 v136, -v136, v175, v167
	v_div_fmas_f32 v136, v136, v138, v175
	v_pk_mul_f32 v[192:193], v[102:103], v[174:175] op_sel_hi:[1,0]
	v_div_fixup_f32 v190, v136, v190, 1.0
	v_mul_f32_e32 v138, 0xbfb8aa3b, v192
	v_pk_mul_f32 v[178:179], v[190:191], v[178:179]
	v_exp_f32_e32 v190, v138
	v_mul_f32_e32 v138, 0xbfb8aa3b, v193
	v_exp_f32_e32 v191, v138
	v_lshlrev_b32_e32 v136, 16, v137
	v_and_b32_e32 v137, 0xffff0000, v137
; DI unsigned pk(float lo, float hi) { f32x2 v = {lo, hi}; bf2_t b = __builtin_convertvector(v, bf2_t); return __builtin_bit_cast(unsigned, b); }
; DI float bflo(unsigned w) { return __uint_as_float(w << 16); }
; DI float bfhi(unsigned w) { return __uint_as_float(w & 0xffff0000u); }
; DI float sigmoidf_(float x) { return 1.0f / (1.0f + __expf(-x)); }
; DI void gemm_epilogue(const GemmDesc& g, f32x4 (&acc)[2][2][4][2], int brow, int bcol, int wr, int wc, int fr, int fq) {
;     ...
;           const int row = rowb + ai * HALF + m * 16;
;           float rs;
;           { const float* sp = g.f0 + (size_t)row * 32 + head * 8;
;             const f32x4 s0 = gld<f32x4>(sp); float ssum = (s0[0] + s0[1]) + (s0[2] + s0[3]);
;             if (g.dvshift == 9) { const f32x4 s1 = gld<f32x4>(sp + 4); ssum += (s1[0] + s1[1]) + (s1[2] + s1[3]); }
;             rs = rsqrtf(ssum * (g.dvshift == 9 ? (1.0f / 512.0f) : (1.0f / 256.0f)) + EPS); }
;           bf16_t* op = g.o0 + (size_t)row * N + col;
;           const u32x4 ow = gld<u32x4>(op);
;           const float ru = gld<float>(g.rowscale + row);
;           const f32x4 v0 = acc[ai][bj][m][0] * ru, v1 = acc[ai][bj][m][1] * ru;
;           float o[8] = {bflo(ow.x), bfhi(ow.x), bflo(ow.y), bfhi(ow.y), bflo(ow.z), bfhi(ow.z), bflo(ow.w), bfhi(ow.w)};
; #pragma unroll
;           for (int j = 0; j < 4; ++j) { o[j] = o[j] * rs * g0[j] * v0[j] * sigmoidf_(v0[j]); o[4 + j] = o[4 + j] * rs * g1[j] * v1[j] * sigmoidf_(v1[j]); }
;           u32x4 w; w.x = pk(o[0], o[1]); w.y = pk(o[2], o[3]); w.z = pk(o[4], o[5]); w.w = pk(o[6], o[7]);
;           gst<u32x4>(op, w);
	v_pk_mul_f32 v[136:137], v[148:149], v[136:137] op_sel_hi:[0,1]
	v_pk_add_f32 v[190:191], v[190:191], 1.0 op_sel_hi:[1,0]
	v_pk_mul_f32 v[136:137], v[134:135], v[136:137]
	v_div_scale_f32 v138, s[26:27], v191, v191, 1.0
	v_rcp_f32_e32 v167, v138
	v_pk_mul_f32 v[136:137], v[192:193], v[136:137]
	v_fma_f32 v175, -v138, v167, 1.0
	v_fmac_f32_e32 v167, v175, v167
	v_div_scale_f32 v175, vcc, 1.0, v191, 1.0
	v_mul_f32_e32 v192, v175, v167
	v_fma_f32 v193, -v138, v192, v175
	v_fmac_f32_e32 v192, v193, v167
	v_fma_f32 v138, -v138, v192, v175
	v_div_fmas_f32 v138, v138, v167, v192
	v_div_fixup_f32 v191, v138, v191, 1.0
	v_div_scale_f32 v138, s[26:27], v190, v190, 1.0
	v_rcp_f32_e32 v167, v138
	s_nop 0
	v_fma_f32 v175, -v138, v167, 1.0
	v_fmac_f32_e32 v167, v175, v167
	v_div_scale_f32 v175, vcc, 1.0, v190, 1.0
	v_mul_f32_e32 v192, v175, v167
	v_fma_f32 v193, -v138, v192, v175
	v_fmac_f32_e32 v192, v193, v167
	v_fma_f32 v138, -v138, v192, v175
	v_div_fmas_f32 v138, v138, v167, v192
	v_div_fixup_f32 v190, v138, v190, 1.0
	v_pk_mul_f32 v[190:191], v[190:191], v[136:137]
	v_lshlrev_b32_e32 v136, 16, v139
	v_and_b32_e32 v137, 0xffff0000, v139
	v_pk_mul_f32 v[136:137], v[148:149], v[136:137] op_sel_hi:[0,1]
	v_pk_mul_f32 v[138:139], v[98:99], v[174:175] op_sel_hi:[1,0]
	v_pk_mul_f32 v[136:137], v[130:131], v[136:137]
	v_mul_f32_e32 v167, 0xbfb8aa3b, v138
	v_pk_mul_f32 v[136:137], v[138:139], v[136:137]
	v_mul_f32_e32 v138, 0xbfb8aa3b, v139
	v_exp_f32_e32 v174, v167
	v_exp_f32_e32 v175, v138
	s_nop 0
	v_pk_add_f32 v[138:139], v[174:175], 1.0 op_sel_hi:[1,0]
	s_nop 0
	v_div_scale_f32 v148, s[26:27], v139, v139, 1.0
	v_rcp_f32_e32 v167, v148
	s_nop 0
	v_fma_f32 v174, -v148, v167, 1.0
	v_fmac_f32_e32 v167, v174, v167
	v_div_scale_f32 v174, vcc, 1.0, v139, 1.0
	v_mul_f32_e32 v175, v174, v167
	v_fma_f32 v192, -v148, v175, v174
	v_fmac_f32_e32 v175, v192, v167
	v_fma_f32 v148, -v148, v175, v174
	v_div_fmas_f32 v148, v148, v167, v175
	v_div_fixup_f32 v139, v148, v139, 1.0
	v_div_scale_f32 v148, s[26:27], v138, v138, 1.0
	v_rcp_f32_e32 v167, v148
	s_mov_b32 s26, 0x3b800000
	s_mov_b32 s27, 0x3b800000
	v_fma_f32 v174, -v148, v167, 1.0
	v_fmac_f32_e32 v167, v174, v167
	v_div_scale_f32 v174, vcc, 1.0, v138, 1.0
	v_mul_f32_e32 v175, v174, v167
	v_fma_f32 v192, -v148, v175, v174
	v_fmac_f32_e32 v175, v192, v167
	v_fma_f32 v148, -v148, v175, v174
	v_div_fmas_f32 v148, v148, v167, v175
	v_div_fixup_f32 v138, v148, v138, 1.0
	v_pk_mul_f32 v[174:175], v[138:139], v[136:137]
	v_cvt_pk_bf16_f32 v136, v176, v177
	v_cvt_pk_bf16_f32 v137, v190, v191
	v_cvt_pk_bf16_f32 v138, v178, v179
	v_cvt_pk_bf16_f32 v139, v174, v175
	global_store_dwordx4 v[172:173], v[136:139], off
	s_and_b64 vcc, exec, s[44:45]
	s_nop 0
	v_add_u32_e32 v136, 0x80, v166
	v_ashrrev_i32_e32 v137, 31, v136
	v_lshlrev_b64 v[138:139], 7, v[136:137]
	v_lshl_add_u64 v[190:191], s[66:67], 0, v[138:139]
	v_lshl_add_u64 v[174:175], v[180:181], 2, v[190:191]
	global_load_dwordx4 v[176:179], v[174:175], off
	global_load_dwordx4 v[232:235], v[174:175], off offset:16
	v_mad_u64_u32 v[238:239], s[100:101], v136, s70, 0
	v_mov_b32_e32 v240, v239
	v_mad_u64_u32 v[240:241], s[100:101], v137, s70, v[240:241]
	v_mov_b32_e32 v239, v240
	v_lshl_add_u64 v[238:239], v[238:239], 1, s[64:65]
	v_lshl_add_u64 v[236:237], v[164:165], 1, v[238:239]
	global_load_dwordx4 v[242:245], v[236:237], off
	global_load_dword v246, v[140:141], off offset:512
	s_waitcnt vmcnt(0)
	v_mov_b32_e32 v138, v177
	v_mov_b32_e32 v139, v178
	v_mov_b32_e32 v177, v179
	v_pk_add_f32 v[138:139], v[138:139], v[176:177]
	s_nop 0
	v_pk_add_f32 v[138:139], v[138:139], v[138:139] op_sel:[0,1] op_sel_hi:[1,0]
	s_cbranch_vccnz .LBB0_229
	v_mov_b64_e32 v[174:175], v[232:233]
	v_mov_b64_e32 v[176:177], v[234:235]
	s_mov_b32 s27, 0x3b000000
	v_mov_b32_e32 v178, v175
	v_mov_b32_e32 v179, v176
	v_mov_b32_e32 v175, v177
	v_pk_add_f32 v[174:175], v[178:179], v[174:175]
	s_nop 0
	v_add_f32_e32 v139, v174, v175
	v_add_f32_e32 v138, v138, v139
.LBB0_229:
	v_fma_f32 v138, s27, v138, v204
	v_cmp_gt_f32_e32 vcc, s33, v138
	v_mul_f32_e32 v139, 0x4b800000, v138
	s_nop 0
	v_cndmask_b32_e32 v138, v138, v139, vcc
	v_rsq_f32_e32 v138, v138
	s_nop 0
	v_mul_f32_e32 v139, 0x45800000, v138
	v_cndmask_b32_e32 v148, v138, v139, vcc
	v_mov_b64_e32 v[174:175], v[236:237]
	v_mov_b64_e32 v[136:137], v[242:243]
	v_mov_b64_e32 v[138:139], v[244:245]
	v_mov_b32_e32 v176, v246
	v_lshlrev_b32_e32 v178, 16, v136
	v_pk_mul_f32 v[192:193], v[92:93], v[176:177] op_sel_hi:[1,0]
	v_and_b32_e32 v179, 0xffff0000, v136
	v_mul_f32_e32 v136, 0xbfb8aa3b, v192
	v_exp_f32_e32 v194, v136
	v_mul_f32_e32 v136, 0xbfb8aa3b, v193
	v_exp_f32_e32 v195, v136
	v_pk_mul_f32 v[178:179], v[148:149], v[178:179] op_sel_hi:[0,1]
	v_pk_mul_f32 v[178:179], v[132:133], v[178:179]
	s_nop 0
	v_pk_mul_f32 v[178:179], v[192:193], v[178:179]
	v_pk_add_f32 v[192:193], v[194:195], 1.0 op_sel_hi:[1,0]
	s_nop 0
	v_div_scale_f32 v136, vcc, v193, v193, 1.0
	v_rcp_f32_e32 v167, v136
	s_nop 0
	v_fma_f32 v177, -v136, v167, 1.0
	v_fmac_f32_e32 v167, v177, v167
	v_div_scale_f32 v177, vcc, 1.0, v193, 1.0
	v_mul_f32_e32 v194, v177, v167
	v_fma_f32 v195, -v136, v194, v177
	v_fmac_f32_e32 v194, v195, v167
	v_fma_f32 v136, -v136, v194, v177
	v_div_fmas_f32 v136, v136, v167, v194
	v_div_fixup_f32 v193, v136, v193, 1.0
	v_div_scale_f32 v136, vcc, v192, v192, 1.0
	v_rcp_f32_e32 v167, v136
	s_nop 0
	v_fma_f32 v177, -v136, v167, 1.0
	v_fmac_f32_e32 v167, v177, v167
	v_div_scale_f32 v177, vcc, 1.0, v192, 1.0
	v_mul_f32_e32 v194, v177, v167
	v_fma_f32 v195, -v136, v194, v177
	v_fmac_f32_e32 v194, v195, v167
	v_fma_f32 v136, -v136, v194, v177
; DI unsigned pk(float lo, float hi) { f32x2 v = {lo, hi}; bf2_t b = __builtin_convertvector(v, bf2_t); return __builtin_bit_cast(unsigned, b); }
; DI float bflo(unsigned w) { return __uint_as_float(w << 16); }
; DI float bfhi(unsigned w) { return __uint_as_float(w & 0xffff0000u); }
; DI float sigmoidf_(float x) { return 1.0f / (1.0f + __expf(-x)); }
; DI void gemm_epilogue(const GemmDesc& g, f32x4 (&acc)[2][2][4][2], int brow, int bcol, int wr, int wc, int fr, int fq) {
;     ...
;           const int row = rowb + ai * HALF + m * 16;
;           float rs;
;           { const float* sp = g.f0 + (size_t)row * 32 + head * 8;
;             const f32x4 s0 = gld<f32x4>(sp); float ssum = (s0[0] + s0[1]) + (s0[2] + s0[3]);
;             if (g.dvshift == 9) { const f32x4 s1 = gld<f32x4>(sp + 4); ssum += (s1[0] + s1[1]) + (s1[2] + s1[3]); }
;             rs = rsqrtf(ssum * (g.dvshift == 9 ? (1.0f / 512.0f) : (1.0f / 256.0f)) + EPS); }
;           bf16_t* op = g.o0 + (size_t)row * N + col;
;           const u32x4 ow = gld<u32x4>(op);
;           const float ru = gld<float>(g.rowscale + row);
;           const f32x4 v0 = acc[ai][bj][m][0] * ru, v1 = acc[ai][bj][m][1] * ru;
;           float o[8] = {bflo(ow.x), bfhi(ow.x), bflo(ow.y), bfhi(ow.y), bflo(ow.z), bfhi(ow.z), bflo(ow.w), bfhi(ow.w)};
; #pragma unroll
;           for (int j = 0; j < 4; ++j) { o[j] = o[j] * rs * g0[j] * v0[j] * sigmoidf_(v0[j]); o[4 + j] = o[4 + j] * rs * g1[j] * v1[j] * sigmoidf_(v1[j]); }
;           u32x4 w; w.x = pk(o[0], o[1]); w.y = pk(o[2], o[3]); w.z = pk(o[4], o[5]); w.w = pk(o[6], o[7]);
;           gst<u32x4>(op, w);
	v_div_fmas_f32 v136, v136, v167, v194
	v_pk_mul_f32 v[194:195], v[88:89], v[176:177] op_sel_hi:[1,0]
	v_div_fixup_f32 v192, v136, v192, 1.0
	v_mul_f32_e32 v136, 0xbfb8aa3b, v194
	v_exp_f32_e32 v196, v136
	v_mul_f32_e32 v136, 0xbfb8aa3b, v195
	v_exp_f32_e32 v197, v136
	v_pk_mul_f32 v[178:179], v[192:193], v[178:179]
	v_lshlrev_b32_e32 v192, 16, v138
	v_and_b32_e32 v193, 0xffff0000, v138
	v_pk_mul_f32 v[192:193], v[148:149], v[192:193] op_sel_hi:[0,1]
	v_pk_mul_f32 v[192:193], v[128:129], v[192:193]
	s_nop 0
	v_pk_mul_f32 v[192:193], v[194:195], v[192:193]
	v_pk_add_f32 v[194:195], v[196:197], 1.0 op_sel_hi:[1,0]
	s_nop 0
	v_div_scale_f32 v136, vcc, v195, v195, 1.0
	v_rcp_f32_e32 v138, v136
	s_nop 0
	v_fma_f32 v167, -v136, v138, 1.0
	v_fmac_f32_e32 v138, v167, v138
	v_div_scale_f32 v167, vcc, 1.0, v195, 1.0
	v_mul_f32_e32 v177, v167, v138
	v_fma_f32 v196, -v136, v177, v167
	v_fmac_f32_e32 v177, v196, v138
	v_fma_f32 v136, -v136, v177, v167
	v_div_fmas_f32 v136, v136, v138, v177
	v_div_fixup_f32 v195, v136, v195, 1.0
	v_div_scale_f32 v136, vcc, v194, v194, 1.0
	v_rcp_f32_e32 v138, v136
	s_nop 0
	v_fma_f32 v167, -v136, v138, 1.0
	v_fmac_f32_e32 v138, v167, v138
	v_div_scale_f32 v167, vcc, 1.0, v194, 1.0
	v_mul_f32_e32 v177, v167, v138
	v_fma_f32 v196, -v136, v177, v167
	v_fmac_f32_e32 v177, v196, v138
	v_fma_f32 v136, -v136, v177, v167
	v_div_fmas_f32 v136, v136, v138, v177
	v_pk_mul_f32 v[196:197], v[94:95], v[176:177] op_sel_hi:[1,0]
	v_div_fixup_f32 v194, v136, v194, 1.0
	v_mul_f32_e32 v138, 0xbfb8aa3b, v196
	v_pk_mul_f32 v[192:193], v[194:195], v[192:193]
	v_exp_f32_e32 v194, v138
	v_mul_f32_e32 v138, 0xbfb8aa3b, v197
	v_exp_f32_e32 v195, v138
	v_lshlrev_b32_e32 v136, 16, v137
	v_and_b32_e32 v137, 0xffff0000, v137
	v_pk_mul_f32 v[136:137], v[148:149], v[136:137] op_sel_hi:[0,1]
	v_pk_add_f32 v[194:195], v[194:195], 1.0 op_sel_hi:[1,0]
	v_pk_mul_f32 v[136:137], v[134:135], v[136:137]
	v_div_scale_f32 v138, vcc, v195, v195, 1.0
	v_rcp_f32_e32 v167, v138
	v_pk_mul_f32 v[136:137], v[196:197], v[136:137]
	v_fma_f32 v177, -v138, v167, 1.0
	v_fmac_f32_e32 v167, v177, v167
	v_div_scale_f32 v177, vcc, 1.0, v195, 1.0
	v_mul_f32_e32 v196, v177, v167
	v_fma_f32 v197, -v138, v196, v177
	v_fmac_f32_e32 v196, v197, v167
	v_fma_f32 v138, -v138, v196, v177
	v_div_fmas_f32 v138, v138, v167, v196
	v_div_fixup_f32 v195, v138, v195, 1.0
	v_div_scale_f32 v138, vcc, v194, v194, 1.0
	v_rcp_f32_e32 v167, v138
	s_nop 0
	v_fma_f32 v177, -v138, v167, 1.0
	v_fmac_f32_e32 v167, v177, v167
	v_div_scale_f32 v177, vcc, 1.0, v194, 1.0
	v_mul_f32_e32 v196, v177, v167
	v_fma_f32 v197, -v138, v196, v177
	v_fmac_f32_e32 v196, v197, v167
	v_fma_f32 v138, -v138, v196, v177
	v_div_fmas_f32 v138, v138, v167, v196
	v_div_fixup_f32 v194, v138, v194, 1.0
	v_pk_mul_f32 v[194:195], v[194:195], v[136:137]
	v_lshlrev_b32_e32 v136, 16, v139
	v_and_b32_e32 v137, 0xffff0000, v139
	v_pk_mul_f32 v[136:137], v[148:149], v[136:137] op_sel_hi:[0,1]
	v_pk_mul_f32 v[138:139], v[90:91], v[176:177] op_sel_hi:[1,0]
	v_pk_mul_f32 v[136:137], v[130:131], v[136:137]
	v_mul_f32_e32 v167, 0xbfb8aa3b, v138
	v_pk_mul_f32 v[136:137], v[138:139], v[136:137]
	v_mul_f32_e32 v138, 0xbfb8aa3b, v139
	v_exp_f32_e32 v176, v167
	v_exp_f32_e32 v177, v138
	s_nop 0
	v_pk_add_f32 v[138:139], v[176:177], 1.0 op_sel_hi:[1,0]
	s_nop 0
	v_div_scale_f32 v148, vcc, v139, v139, 1.0
	v_rcp_f32_e32 v167, v148
	s_nop 0
	v_fma_f32 v176, -v148, v167, 1.0
	v_fmac_f32_e32 v167, v176, v167
	v_div_scale_f32 v176, vcc, 1.0, v139, 1.0
	v_mul_f32_e32 v177, v176, v167
	v_fma_f32 v196, -v148, v177, v176
	v_fmac_f32_e32 v177, v196, v167
	v_fma_f32 v148, -v148, v177, v176
	v_div_fmas_f32 v148, v148, v167, v177
	v_div_fixup_f32 v139, v148, v139, 1.0
	v_div_scale_f32 v148, vcc, v138, v138, 1.0
	v_rcp_f32_e32 v167, v148
	s_nop 0
	v_fma_f32 v176, -v148, v167, 1.0
	v_fmac_f32_e32 v167, v176, v167
	v_div_scale_f32 v176, vcc, 1.0, v138, 1.0
	v_mul_f32_e32 v177, v176, v167
	v_fma_f32 v196, -v148, v177, v176
	v_fmac_f32_e32 v177, v196, v167
	v_fma_f32 v148, -v148, v177, v176
	v_div_fmas_f32 v148, v148, v167, v177
	v_div_fixup_f32 v138, v148, v138, 1.0
	v_pk_mul_f32 v[176:177], v[138:139], v[136:137]
	v_cvt_pk_bf16_f32 v136, v178, v179
	v_cvt_pk_bf16_f32 v137, v194, v195
	v_cvt_pk_bf16_f32 v138, v192, v193
	v_cvt_pk_bf16_f32 v139, v176, v177
	global_store_dwordx4 v[174:175], v[136:139], off
	s_and_b64 vcc, exec, s[44:45]
	s_nop 0
	v_add_u32_e32 v136, 0x90, v166
	v_ashrrev_i32_e32 v137, 31, v136
	v_lshlrev_b64 v[138:139], 7, v[136:137]
	v_lshl_add_u64 v[192:193], s[66:67], 0, v[138:139]
	v_lshl_add_u64 v[176:177], v[180:181], 2, v[192:193]
	global_load_dwordx4 v[194:197], v[176:177], off
	global_load_dwordx4 v[232:235], v[176:177], off offset:16
	v_mad_u64_u32 v[238:239], s[100:101], v136, s70, 0
	v_mov_b32_e32 v240, v239
	v_mad_u64_u32 v[240:241], s[100:101], v137, s70, v[240:241]
	v_mov_b32_e32 v239, v240
	v_lshl_add_u64 v[238:239], v[238:239], 1, s[64:65]
	v_lshl_add_u64 v[236:237], v[164:165], 1, v[238:239]
	global_load_dwordx4 v[242:245], v[236:237], off
	global_load_dword v246, v[140:141], off offset:576
	s_waitcnt vmcnt(0)
	v_mov_b32_e32 v138, v195
	v_mov_b32_e32 v139, v196
	v_mov_b32_e32 v195, v197
	v_pk_add_f32 v[138:139], v[138:139], v[194:195]
	s_nop 0
	v_pk_add_f32 v[138:139], v[138:139], v[138:139] op_sel:[0,1] op_sel_hi:[1,0]
	s_cbranch_vccnz .LBB0_231
	v_mov_b64_e32 v[176:177], v[232:233]
	v_mov_b64_e32 v[178:179], v[234:235]
	s_mov_b32 s26, 0x3b000000
	v_mov_b32_e32 v194, v177
	v_mov_b32_e32 v195, v178
	v_mov_b32_e32 v177, v179
	v_pk_add_f32 v[176:177], v[194:195], v[176:177]
	s_nop 0
	v_add_f32_e32 v139, v176, v177
	v_add_f32_e32 v138, v138, v139
; DI unsigned pk(float lo, float hi) { f32x2 v = {lo, hi}; bf2_t b = __builtin_convertvector(v, bf2_t); return __builtin_bit_cast(unsigned, b); }
; DI float bflo(unsigned w) { return __uint_as_float(w << 16); }
; DI float bfhi(unsigned w) { return __uint_as_float(w & 0xffff0000u); }
; DI float sigmoidf_(float x) { return 1.0f / (1.0f + __expf(-x)); }
; DI void gemm_epilogue(const GemmDesc& g, f32x4 (&acc)[2][2][4][2], int brow, int bcol, int wr, int wc, int fr, int fq) {
;     ...
;           const int row = rowb + ai * HALF + m * 16;
;           float rs;
;           { const float* sp = g.f0 + (size_t)row * 32 + head * 8;
;             const f32x4 s0 = gld<f32x4>(sp); float ssum = (s0[0] + s0[1]) + (s0[2] + s0[3]);
;             if (g.dvshift == 9) { const f32x4 s1 = gld<f32x4>(sp + 4); ssum += (s1[0] + s1[1]) + (s1[2] + s1[3]); }
;             rs = rsqrtf(ssum * (g.dvshift == 9 ? (1.0f / 512.0f) : (1.0f / 256.0f)) + EPS); }
;           bf16_t* op = g.o0 + (size_t)row * N + col;
;           const u32x4 ow = gld<u32x4>(op);
;           const float ru = gld<float>(g.rowscale + row);
;           const f32x4 v0 = acc[ai][bj][m][0] * ru, v1 = acc[ai][bj][m][1] * ru;
;           float o[8] = {bflo(ow.x), bfhi(ow.x), bflo(ow.y), bfhi(ow.y), bflo(ow.z), bfhi(ow.z), bflo(ow.w), bfhi(ow.w)};
; #pragma unroll
;           for (int j = 0; j < 4; ++j) { o[j] = o[j] * rs * g0[j] * v0[j] * sigmoidf_(v0[j]); o[4 + j] = o[4 + j] * rs * g1[j] * v1[j] * sigmoidf_(v1[j]); }
;           u32x4 w; w.x = pk(o[0], o[1]); w.y = pk(o[2], o[3]); w.z = pk(o[4], o[5]); w.w = pk(o[6], o[7]);
;           gst<u32x4>(op, w);
.LBB0_231:
	v_fma_f32 v138, s26, v138, v204
	v_cmp_gt_f32_e32 vcc, s33, v138
	v_mul_f32_e32 v139, 0x4b800000, v138
	s_nop 0
	v_cndmask_b32_e32 v138, v138, v139, vcc
	v_rsq_f32_e32 v138, v138
	s_nop 0
	v_mul_f32_e32 v139, 0x45800000, v138
	v_cndmask_b32_e32 v148, v138, v139, vcc
	v_mov_b64_e32 v[176:177], v[236:237]
	v_mov_b64_e32 v[136:137], v[242:243]
	v_mov_b64_e32 v[138:139], v[244:245]
	v_mov_b32_e32 v178, v246
	v_lshlrev_b32_e32 v194, 16, v136
	v_pk_mul_f32 v[196:197], v[84:85], v[178:179] op_sel_hi:[1,0]
	v_and_b32_e32 v195, 0xffff0000, v136
	v_mul_f32_e32 v136, 0xbfb8aa3b, v196
	v_exp_f32_e32 v198, v136
	v_mul_f32_e32 v136, 0xbfb8aa3b, v197
	v_exp_f32_e32 v199, v136
	v_pk_mul_f32 v[194:195], v[148:149], v[194:195] op_sel_hi:[0,1]
	v_pk_mul_f32 v[194:195], v[132:133], v[194:195]
	s_nop 0
	v_pk_mul_f32 v[194:195], v[196:197], v[194:195]
	v_pk_add_f32 v[196:197], v[198:199], 1.0 op_sel_hi:[1,0]
	s_nop 0
	v_div_scale_f32 v136, s[26:27], v197, v197, 1.0
	v_rcp_f32_e32 v167, v136
	s_nop 0
	v_fma_f32 v179, -v136, v167, 1.0
	v_fmac_f32_e32 v167, v179, v167
	v_div_scale_f32 v179, vcc, 1.0, v197, 1.0
	v_mul_f32_e32 v198, v179, v167
	v_fma_f32 v199, -v136, v198, v179
	v_fmac_f32_e32 v198, v199, v167
	v_fma_f32 v136, -v136, v198, v179
	v_div_fmas_f32 v136, v136, v167, v198
	v_div_fixup_f32 v197, v136, v197, 1.0
	v_div_scale_f32 v136, s[26:27], v196, v196, 1.0
	v_rcp_f32_e32 v167, v136
	s_nop 0
	v_fma_f32 v179, -v136, v167, 1.0
	v_fmac_f32_e32 v167, v179, v167
	v_div_scale_f32 v179, vcc, 1.0, v196, 1.0
	v_mul_f32_e32 v198, v179, v167
	v_fma_f32 v199, -v136, v198, v179
	v_fmac_f32_e32 v198, v199, v167
	v_fma_f32 v136, -v136, v198, v179
	v_div_fmas_f32 v136, v136, v167, v198
	v_pk_mul_f32 v[198:199], v[80:81], v[178:179] op_sel_hi:[1,0]
	v_div_fixup_f32 v196, v136, v196, 1.0
	v_mul_f32_e32 v136, 0xbfb8aa3b, v198
	v_exp_f32_e32 v200, v136
	v_mul_f32_e32 v136, 0xbfb8aa3b, v199
	v_exp_f32_e32 v201, v136
	v_pk_mul_f32 v[194:195], v[196:197], v[194:195]
	v_lshlrev_b32_e32 v196, 16, v138
	v_and_b32_e32 v197, 0xffff0000, v138
	v_pk_mul_f32 v[196:197], v[148:149], v[196:197] op_sel_hi:[0,1]
	v_pk_mul_f32 v[196:197], v[128:129], v[196:197]
	s_nop 0
	v_pk_mul_f32 v[196:197], v[198:199], v[196:197]
	v_pk_add_f32 v[198:199], v[200:201], 1.0 op_sel_hi:[1,0]
	s_nop 0
	v_div_scale_f32 v136, s[26:27], v199, v199, 1.0
	v_rcp_f32_e32 v138, v136
	s_nop 0
	v_fma_f32 v167, -v136, v138, 1.0
	v_fmac_f32_e32 v138, v167, v138
	v_div_scale_f32 v167, vcc, 1.0, v199, 1.0
	v_mul_f32_e32 v179, v167, v138
	v_fma_f32 v200, -v136, v179, v167
	v_fmac_f32_e32 v179, v200, v138
	v_fma_f32 v136, -v136, v179, v167
	v_div_fmas_f32 v136, v136, v138, v179
	v_div_fixup_f32 v199, v136, v199, 1.0
	v_div_scale_f32 v136, s[26:27], v198, v198, 1.0
	v_rcp_f32_e32 v138, v136
	s_nop 0
	v_fma_f32 v167, -v136, v138, 1.0
	v_fmac_f32_e32 v138, v167, v138
	v_div_scale_f32 v167, vcc, 1.0, v198, 1.0
	v_mul_f32_e32 v179, v167, v138
	v_fma_f32 v200, -v136, v179, v167
	v_fmac_f32_e32 v179, v200, v138
	v_fma_f32 v136, -v136, v179, v167
	v_div_fmas_f32 v136, v136, v138, v179
	v_pk_mul_f32 v[200:201], v[86:87], v[178:179] op_sel_hi:[1,0]
	v_div_fixup_f32 v198, v136, v198, 1.0
	v_mul_f32_e32 v138, 0xbfb8aa3b, v200
	v_pk_mul_f32 v[196:197], v[198:199], v[196:197]
	v_exp_f32_e32 v198, v138
	v_mul_f32_e32 v138, 0xbfb8aa3b, v201
	v_exp_f32_e32 v199, v138
	v_lshlrev_b32_e32 v136, 16, v137
	v_and_b32_e32 v137, 0xffff0000, v137
	v_pk_mul_f32 v[136:137], v[148:149], v[136:137] op_sel_hi:[0,1]
	v_pk_add_f32 v[198:199], v[198:199], 1.0 op_sel_hi:[1,0]
	v_pk_mul_f32 v[136:137], v[134:135], v[136:137]
	v_div_scale_f32 v138, s[26:27], v199, v199, 1.0
	v_rcp_f32_e32 v167, v138
	v_pk_mul_f32 v[136:137], v[200:201], v[136:137]
	v_fma_f32 v179, -v138, v167, 1.0
	v_fmac_f32_e32 v167, v179, v167
	v_div_scale_f32 v179, vcc, 1.0, v199, 1.0
	v_mul_f32_e32 v200, v179, v167
	v_fma_f32 v201, -v138, v200, v179
	v_fmac_f32_e32 v200, v201, v167
	v_fma_f32 v138, -v138, v200, v179
	v_div_fmas_f32 v138, v138, v167, v200
	v_div_fixup_f32 v199, v138, v199, 1.0
	v_div_scale_f32 v138, s[26:27], v198, v198, 1.0
	v_rcp_f32_e32 v167, v138
	s_nop 0
	v_fma_f32 v179, -v138, v167, 1.0
	v_fmac_f32_e32 v167, v179, v167
	v_div_scale_f32 v179, vcc, 1.0, v198, 1.0
	v_mul_f32_e32 v200, v179, v167
	v_fma_f32 v201, -v138, v200, v179
	v_fmac_f32_e32 v200, v201, v167
	v_fma_f32 v138, -v138, v200, v179
	v_div_fmas_f32 v138, v138, v167, v200
	v_div_fixup_f32 v198, v138, v198, 1.0
	v_pk_mul_f32 v[198:199], v[198:199], v[136:137]
	v_lshlrev_b32_e32 v136, 16, v139
	v_and_b32_e32 v137, 0xffff0000, v139
	v_pk_mul_f32 v[136:137], v[148:149], v[136:137] op_sel_hi:[0,1]
	v_pk_mul_f32 v[138:139], v[82:83], v[178:179] op_sel_hi:[1,0]
	v_pk_mul_f32 v[136:137], v[130:131], v[136:137]
	v_mul_f32_e32 v167, 0xbfb8aa3b, v138
	v_pk_mul_f32 v[136:137], v[138:139], v[136:137]
	v_mul_f32_e32 v138, 0xbfb8aa3b, v139
	v_exp_f32_e32 v178, v167
	v_exp_f32_e32 v179, v138
	s_nop 0
	v_pk_add_f32 v[138:139], v[178:179], 1.0 op_sel_hi:[1,0]
	s_nop 0
	v_div_scale_f32 v148, s[26:27], v139, v139, 1.0
	v_rcp_f32_e32 v167, v148
	s_nop 0
	v_fma_f32 v178, -v148, v167, 1.0
	v_fmac_f32_e32 v167, v178, v167
	v_div_scale_f32 v178, vcc, 1.0, v139, 1.0
	v_mul_f32_e32 v179, v178, v167
	v_fma_f32 v200, -v148, v179, v178
	v_fmac_f32_e32 v179, v200, v167
	v_fma_f32 v148, -v148, v179, v178
	v_div_fmas_f32 v148, v148, v167, v179
	v_div_fixup_f32 v139, v148, v139, 1.0
	v_div_scale_f32 v148, s[26:27], v138, v138, 1.0
	v_rcp_f32_e32 v167, v148
	s_mov_b32 s26, 0x3b800000
	s_mov_b32 s27, 0x3b800000
	v_fma_f32 v178, -v148, v167, 1.0
	v_fmac_f32_e32 v167, v178, v167
	v_div_scale_f32 v178, vcc, 1.0, v138, 1.0
	v_mul_f32_e32 v179, v178, v167
	v_fma_f32 v200, -v148, v179, v178
	v_fmac_f32_e32 v179, v200, v167
	v_fma_f32 v148, -v148, v179, v178
	v_div_fmas_f32 v148, v148, v167, v179
	v_div_fixup_f32 v138, v148, v138, 1.0
	v_pk_mul_f32 v[178:179], v[138:139], v[136:137]
	v_cvt_pk_bf16_f32 v136, v194, v195
	v_cvt_pk_bf16_f32 v137, v198, v199
	v_cvt_pk_bf16_f32 v138, v196, v197
	v_cvt_pk_bf16_f32 v139, v178, v179
	global_store_dwordx4 v[176:177], v[136:139], off
	s_and_b64 vcc, exec, s[44:45]
	s_nop 0
	v_add_u32_e32 v136, 0xa0, v166
	v_ashrrev_i32_e32 v137, 31, v136
	v_lshlrev_b64 v[138:139], 7, v[136:137]
	v_lshl_add_u64 v[194:195], s[66:67], 0, v[138:139]
	v_lshl_add_u64 v[178:179], v[180:181], 2, v[194:195]
	global_load_dwordx4 v[196:199], v[178:179], off
	global_load_dwordx4 v[232:235], v[178:179], off offset:16
	v_mad_u64_u32 v[238:239], s[100:101], v136, s70, 0
	v_mov_b32_e32 v240, v239
	v_mad_u64_u32 v[240:241], s[100:101], v137, s70, v[240:241]
	v_mov_b32_e32 v239, v240
	v_lshl_add_u64 v[238:239], v[238:239], 1, s[64:65]
	v_lshl_add_u64 v[236:237], v[164:165], 1, v[238:239]
	global_load_dwordx4 v[242:245], v[236:237], off
	global_load_dword v246, v[140:141], off offset:640
	s_waitcnt vmcnt(0)
; DI unsigned pk(float lo, float hi) { f32x2 v = {lo, hi}; bf2_t b = __builtin_convertvector(v, bf2_t); return __builtin_bit_cast(unsigned, b); }
; DI float bflo(unsigned w) { return __uint_as_float(w << 16); }
; DI float bfhi(unsigned w) { return __uint_as_float(w & 0xffff0000u); }
; DI float sigmoidf_(float x) { return 1.0f / (1.0f + __expf(-x)); }
; DI void gemm_epilogue(const GemmDesc& g, f32x4 (&acc)[2][2][4][2], int brow, int bcol, int wr, int wc, int fr, int fq) {
;     ...
;           const int row = rowb + ai * HALF + m * 16;
;           float rs;
;           { const float* sp = g.f0 + (size_t)row * 32 + head * 8;
;             const f32x4 s0 = gld<f32x4>(sp); float ssum = (s0[0] + s0[1]) + (s0[2] + s0[3]);
;             if (g.dvshift == 9) { const f32x4 s1 = gld<f32x4>(sp + 4); ssum += (s1[0] + s1[1]) + (s1[2] + s1[3]); }
;             rs = rsqrtf(ssum * (g.dvshift == 9 ? (1.0f / 512.0f) : (1.0f / 256.0f)) + EPS); }
;           bf16_t* op = g.o0 + (size_t)row * N + col;
;           const u32x4 ow = gld<u32x4>(op);
;           const float ru = gld<float>(g.rowscale + row);
;           const f32x4 v0 = acc[ai][bj][m][0] * ru, v1 = acc[ai][bj][m][1] * ru;
;           float o[8] = {bflo(ow.x), bfhi(ow.x), bflo(ow.y), bfhi(ow.y), bflo(ow.z), bfhi(ow.z), bflo(ow.w), bfhi(ow.w)};
; #pragma unroll
;           for (int j = 0; j < 4; ++j) { o[j] = o[j] * rs * g0[j] * v0[j] * sigmoidf_(v0[j]); o[4 + j] = o[4 + j] * rs * g1[j] * v1[j] * sigmoidf_(v1[j]); }
;           u32x4 w; w.x = pk(o[0], o[1]); w.y = pk(o[2], o[3]); w.z = pk(o[4], o[5]); w.w = pk(o[6], o[7]);
;           gst<u32x4>(op, w);
	v_mov_b32_e32 v138, v197
	v_mov_b32_e32 v139, v198
	v_mov_b32_e32 v197, v199
	v_pk_add_f32 v[138:139], v[138:139], v[196:197]
	s_nop 0
	v_pk_add_f32 v[138:139], v[138:139], v[138:139] op_sel:[0,1] op_sel_hi:[1,0]
	s_cbranch_vccnz .LBB0_233
	v_mov_b64_e32 v[196:197], v[232:233]
	v_mov_b64_e32 v[198:199], v[234:235]
	s_mov_b32 s27, 0x3b000000
	v_mov_b32_e32 v178, v197
	v_mov_b32_e32 v179, v198
	v_mov_b32_e32 v197, v199
	v_pk_add_f32 v[178:179], v[178:179], v[196:197]
	s_nop 0
	v_add_f32_e32 v139, v178, v179
	v_add_f32_e32 v138, v138, v139
.LBB0_233:
	v_fma_f32 v138, s27, v138, v204
	v_cmp_gt_f32_e32 vcc, s33, v138
	v_mul_f32_e32 v139, 0x4b800000, v138
	s_nop 0
	v_cndmask_b32_e32 v138, v138, v139, vcc
	v_rsq_f32_e32 v138, v138
	s_nop 0
	v_mul_f32_e32 v139, 0x45800000, v138
	v_cndmask_b32_e32 v148, v138, v139, vcc
	v_mov_b64_e32 v[178:179], v[236:237]
	v_mov_b64_e32 v[136:137], v[242:243]
	v_mov_b64_e32 v[138:139], v[244:245]
	v_mov_b32_e32 v196, v246
	v_lshlrev_b32_e32 v198, 16, v136
	v_pk_mul_f32 v[200:201], v[76:77], v[196:197] op_sel_hi:[1,0]
	v_and_b32_e32 v199, 0xffff0000, v136
	v_mul_f32_e32 v136, 0xbfb8aa3b, v200
	v_exp_f32_e32 v202, v136
	v_mul_f32_e32 v136, 0xbfb8aa3b, v201
	v_exp_f32_e32 v203, v136
	v_pk_mul_f32 v[198:199], v[148:149], v[198:199] op_sel_hi:[0,1]
	v_pk_mul_f32 v[198:199], v[132:133], v[198:199]
	s_nop 0
	v_pk_mul_f32 v[198:199], v[200:201], v[198:199]
	v_pk_add_f32 v[200:201], v[202:203], 1.0 op_sel_hi:[1,0]
	s_nop 0
	v_div_scale_f32 v136, vcc, v201, v201, 1.0
	v_rcp_f32_e32 v167, v136
	s_nop 0
	v_fma_f32 v197, -v136, v167, 1.0
	v_fmac_f32_e32 v167, v197, v167
	v_div_scale_f32 v197, vcc, 1.0, v201, 1.0
	v_mul_f32_e32 v202, v197, v167
	v_fma_f32 v203, -v136, v202, v197
	v_fmac_f32_e32 v202, v203, v167
	v_fma_f32 v136, -v136, v202, v197
	v_div_fmas_f32 v136, v136, v167, v202
	v_div_fixup_f32 v201, v136, v201, 1.0
	v_div_scale_f32 v136, vcc, v200, v200, 1.0
	v_rcp_f32_e32 v167, v136
	s_nop 0
	v_fma_f32 v197, -v136, v167, 1.0
	v_fmac_f32_e32 v167, v197, v167
	v_div_scale_f32 v197, vcc, 1.0, v200, 1.0
	v_mul_f32_e32 v202, v197, v167
	v_fma_f32 v203, -v136, v202, v197
	v_fmac_f32_e32 v202, v203, v167
	v_fma_f32 v136, -v136, v202, v197
	v_div_fmas_f32 v136, v136, v167, v202
	v_pk_mul_f32 v[202:203], v[72:73], v[196:197] op_sel_hi:[1,0]
	v_div_fixup_f32 v200, v136, v200, 1.0
	v_mul_f32_e32 v136, 0xbfb8aa3b, v202
	v_exp_f32_e32 v212, v136
	v_mul_f32_e32 v136, 0xbfb8aa3b, v203
	v_exp_f32_e32 v213, v136
	v_pk_mul_f32 v[198:199], v[200:201], v[198:199]
	v_lshlrev_b32_e32 v200, 16, v138
	v_and_b32_e32 v201, 0xffff0000, v138
	v_pk_mul_f32 v[200:201], v[148:149], v[200:201] op_sel_hi:[0,1]
	v_pk_mul_f32 v[200:201], v[128:129], v[200:201]
	s_nop 0
	v_pk_mul_f32 v[200:201], v[202:203], v[200:201]
	v_pk_add_f32 v[202:203], v[212:213], 1.0 op_sel_hi:[1,0]
	s_nop 0
	v_div_scale_f32 v136, vcc, v203, v203, 1.0
	v_rcp_f32_e32 v138, v136
	s_nop 0
	v_fma_f32 v167, -v136, v138, 1.0
	v_fmac_f32_e32 v138, v167, v138
	v_div_scale_f32 v167, vcc, 1.0, v203, 1.0
	v_mul_f32_e32 v197, v167, v138
	v_fma_f32 v212, -v136, v197, v167
	v_fmac_f32_e32 v197, v212, v138
	v_fma_f32 v136, -v136, v197, v167
	v_div_fmas_f32 v136, v136, v138, v197
	v_div_fixup_f32 v203, v136, v203, 1.0
	v_div_scale_f32 v136, vcc, v202, v202, 1.0
	v_rcp_f32_e32 v138, v136
	s_nop 0
	v_fma_f32 v167, -v136, v138, 1.0
	v_fmac_f32_e32 v138, v167, v138
	v_div_scale_f32 v167, vcc, 1.0, v202, 1.0
	v_mul_f32_e32 v197, v167, v138
	v_fma_f32 v212, -v136, v197, v167
	v_fmac_f32_e32 v197, v212, v138
	v_fma_f32 v136, -v136, v197, v167
	v_div_fmas_f32 v136, v136, v138, v197
	v_pk_mul_f32 v[212:213], v[78:79], v[196:197] op_sel_hi:[1,0]
	v_div_fixup_f32 v202, v136, v202, 1.0
	v_mul_f32_e32 v138, 0xbfb8aa3b, v212
	v_pk_mul_f32 v[200:201], v[202:203], v[200:201]
	v_exp_f32_e32 v202, v138
	v_mul_f32_e32 v138, 0xbfb8aa3b, v213
	v_exp_f32_e32 v203, v138
	v_lshlrev_b32_e32 v136, 16, v137
	v_and_b32_e32 v137, 0xffff0000, v137
	v_pk_mul_f32 v[136:137], v[148:149], v[136:137] op_sel_hi:[0,1]
	v_pk_add_f32 v[202:203], v[202:203], 1.0 op_sel_hi:[1,0]
	v_pk_mul_f32 v[136:137], v[134:135], v[136:137]
	v_div_scale_f32 v138, vcc, v203, v203, 1.0
	v_rcp_f32_e32 v167, v138
	v_pk_mul_f32 v[136:137], v[212:213], v[136:137]
	v_fma_f32 v197, -v138, v167, 1.0
	v_fmac_f32_e32 v167, v197, v167
	v_div_scale_f32 v197, vcc, 1.0, v203, 1.0
	v_mul_f32_e32 v212, v197, v167
	v_fma_f32 v213, -v138, v212, v197
	v_fmac_f32_e32 v212, v213, v167
	v_fma_f32 v138, -v138, v212, v197
	v_div_fmas_f32 v138, v138, v167, v212
	v_div_fixup_f32 v203, v138, v203, 1.0
	v_div_scale_f32 v138, vcc, v202, v202, 1.0
	v_rcp_f32_e32 v167, v138
	s_nop 0
	v_fma_f32 v197, -v138, v167, 1.0
	v_fmac_f32_e32 v167, v197, v167
	v_div_scale_f32 v197, vcc, 1.0, v202, 1.0
	v_mul_f32_e32 v212, v197, v167
	v_fma_f32 v213, -v138, v212, v197
	v_fmac_f32_e32 v212, v213, v167
	v_fma_f32 v138, -v138, v212, v197
	v_div_fmas_f32 v138, v138, v167, v212
	v_div_fixup_f32 v202, v138, v202, 1.0
	v_pk_mul_f32 v[202:203], v[202:203], v[136:137]
	v_lshlrev_b32_e32 v136, 16, v139
	v_and_b32_e32 v137, 0xffff0000, v139
	v_pk_mul_f32 v[136:137], v[148:149], v[136:137] op_sel_hi:[0,1]
	v_pk_mul_f32 v[138:139], v[74:75], v[196:197] op_sel_hi:[1,0]
	v_pk_mul_f32 v[136:137], v[130:131], v[136:137]
	v_mul_f32_e32 v167, 0xbfb8aa3b, v138
	v_pk_mul_f32 v[136:137], v[138:139], v[136:137]
	v_mul_f32_e32 v138, 0xbfb8aa3b, v139
	v_exp_f32_e32 v196, v167
	v_exp_f32_e32 v197, v138
	s_nop 0
	v_pk_add_f32 v[138:139], v[196:197], 1.0 op_sel_hi:[1,0]
	s_nop 0
	v_div_scale_f32 v148, vcc, v139, v139, 1.0
	v_rcp_f32_e32 v167, v148
	s_nop 0
	v_fma_f32 v196, -v148, v167, 1.0
	v_fmac_f32_e32 v167, v196, v167
; DI unsigned pk(float lo, float hi) { f32x2 v = {lo, hi}; bf2_t b = __builtin_convertvector(v, bf2_t); return __builtin_bit_cast(unsigned, b); }
; DI float bflo(unsigned w) { return __uint_as_float(w << 16); }
; DI float bfhi(unsigned w) { return __uint_as_float(w & 0xffff0000u); }
; DI float sigmoidf_(float x) { return 1.0f / (1.0f + __expf(-x)); }
; DI void gemm_epilogue(const GemmDesc& g, f32x4 (&acc)[2][2][4][2], int brow, int bcol, int wr, int wc, int fr, int fq) {
;     ...
;           const int row = rowb + ai * HALF + m * 16;
;           float rs;
;           { const float* sp = g.f0 + (size_t)row * 32 + head * 8;
;             const f32x4 s0 = gld<f32x4>(sp); float ssum = (s0[0] + s0[1]) + (s0[2] + s0[3]);
;             if (g.dvshift == 9) { const f32x4 s1 = gld<f32x4>(sp + 4); ssum += (s1[0] + s1[1]) + (s1[2] + s1[3]); }
;             rs = rsqrtf(ssum * (g.dvshift == 9 ? (1.0f / 512.0f) : (1.0f / 256.0f)) + EPS); }
;           bf16_t* op = g.o0 + (size_t)row * N + col;
;           const u32x4 ow = gld<u32x4>(op);
;           const float ru = gld<float>(g.rowscale + row);
;           const f32x4 v0 = acc[ai][bj][m][0] * ru, v1 = acc[ai][bj][m][1] * ru;
;           float o[8] = {bflo(ow.x), bfhi(ow.x), bflo(ow.y), bfhi(ow.y), bflo(ow.z), bfhi(ow.z), bflo(ow.w), bfhi(ow.w)};
; #pragma unroll
;           for (int j = 0; j < 4; ++j) { o[j] = o[j] * rs * g0[j] * v0[j] * sigmoidf_(v0[j]); o[4 + j] = o[4 + j] * rs * g1[j] * v1[j] * sigmoidf_(v1[j]); }
;           u32x4 w; w.x = pk(o[0], o[1]); w.y = pk(o[2], o[3]); w.z = pk(o[4], o[5]); w.w = pk(o[6], o[7]);
;           gst<u32x4>(op, w);
	v_div_scale_f32 v196, vcc, 1.0, v139, 1.0
	v_mul_f32_e32 v197, v196, v167
	v_fma_f32 v212, -v148, v197, v196
	v_fmac_f32_e32 v197, v212, v167
	v_fma_f32 v148, -v148, v197, v196
	v_div_fmas_f32 v148, v148, v167, v197
	v_div_fixup_f32 v139, v148, v139, 1.0
	v_div_scale_f32 v148, vcc, v138, v138, 1.0
	v_rcp_f32_e32 v167, v148
	s_nop 0
	v_fma_f32 v196, -v148, v167, 1.0
	v_fmac_f32_e32 v167, v196, v167
	v_div_scale_f32 v196, vcc, 1.0, v138, 1.0
	v_mul_f32_e32 v197, v196, v167
	v_fma_f32 v212, -v148, v197, v196
	v_fmac_f32_e32 v197, v212, v167
	v_fma_f32 v148, -v148, v197, v196
	v_div_fmas_f32 v148, v148, v167, v197
	v_div_fixup_f32 v138, v148, v138, 1.0
	v_pk_mul_f32 v[196:197], v[138:139], v[136:137]
	v_cvt_pk_bf16_f32 v136, v198, v199
	v_cvt_pk_bf16_f32 v137, v202, v203
	v_cvt_pk_bf16_f32 v138, v200, v201
	v_cvt_pk_bf16_f32 v139, v196, v197
	global_store_dwordx4 v[178:179], v[136:139], off
	s_and_b64 vcc, exec, s[44:45]
	s_nop 0
	v_add_u32_e32 v136, 0xb0, v166
	v_ashrrev_i32_e32 v137, 31, v136
	v_lshlrev_b64 v[138:139], 7, v[136:137]
	v_lshl_add_u64 v[196:197], s[66:67], 0, v[138:139]
	v_lshl_add_u64 v[180:181], v[180:181], 2, v[196:197]
	global_load_dwordx4 v[198:201], v[180:181], off
	global_load_dwordx4 v[232:235], v[180:181], off offset:16
	v_mad_u64_u32 v[238:239], s[100:101], v136, s70, 0
	v_mov_b32_e32 v240, v239
	v_mad_u64_u32 v[240:241], s[100:101], v137, s70, v[240:241]
	v_mov_b32_e32 v239, v240
	v_lshl_add_u64 v[238:239], v[238:239], 1, s[64:65]
	v_lshl_add_u64 v[236:237], v[164:165], 1, v[238:239]
	global_load_dwordx4 v[242:245], v[236:237], off
	global_load_dword v246, v[140:141], off offset:704
	s_waitcnt vmcnt(0)
	v_mov_b32_e32 v138, v199
	v_mov_b32_e32 v139, v200
	v_mov_b32_e32 v199, v201
	v_pk_add_f32 v[138:139], v[138:139], v[198:199]
	s_nop 0
	v_pk_add_f32 v[138:139], v[138:139], v[138:139] op_sel:[0,1] op_sel_hi:[1,0]
	s_cbranch_vccnz .LBB0_235
	v_mov_b64_e32 v[198:199], v[232:233]
	v_mov_b64_e32 v[200:201], v[234:235]
	s_mov_b32 s26, 0x3b000000
	v_mov_b32_e32 v180, v199
	v_mov_b32_e32 v181, v200
	v_mov_b32_e32 v199, v201
	v_pk_add_f32 v[180:181], v[180:181], v[198:199]
	s_nop 0
	v_add_f32_e32 v139, v180, v181
	v_add_f32_e32 v138, v138, v139
; DI unsigned pk(float lo, float hi) { f32x2 v = {lo, hi}; bf2_t b = __builtin_convertvector(v, bf2_t); return __builtin_bit_cast(unsigned, b); }
; DI float bflo(unsigned w) { return __uint_as_float(w << 16); }
; DI float bfhi(unsigned w) { return __uint_as_float(w & 0xffff0000u); }
; DI float sigmoidf_(float x) { return 1.0f / (1.0f + __expf(-x)); }
; DI void gemm_epilogue(const GemmDesc& g, f32x4 (&acc)[2][2][4][2], int brow, int bcol, int wr, int wc, int fr, int fq) {
;     ...
;       const int col = colb + bj * HALF;
;       f32x4 g0 = {1.f, 1.f, 1.f, 1.f}, g1 = g0;
;       if (g.c0) { g0 = gld<f32x4>(g.c0 + (col & dvm)); g1 = gld<f32x4>(g.c0 + (col & dvm) + 4); }
;     ...
;           const int row = rowb + ai * HALF + m * 16;
;           float rs;
;           { const float* sp = g.f0 + (size_t)row * 32 + head * 8;
;             const f32x4 s0 = gld<f32x4>(sp); float ssum = (s0[0] + s0[1]) + (s0[2] + s0[3]);
;             if (g.dvshift == 9) { const f32x4 s1 = gld<f32x4>(sp + 4); ssum += (s1[0] + s1[1]) + (s1[2] + s1[3]); }
;             rs = rsqrtf(ssum * (g.dvshift == 9 ? (1.0f / 512.0f) : (1.0f / 256.0f)) + EPS); }
;           bf16_t* op = g.o0 + (size_t)row * N + col;
;           const u32x4 ow = gld<u32x4>(op);
;           const float ru = gld<float>(g.rowscale + row);
;           const f32x4 v0 = acc[ai][bj][m][0] * ru, v1 = acc[ai][bj][m][1] * ru;
;           float o[8] = {bflo(ow.x), bfhi(ow.x), bflo(ow.y), bfhi(ow.y), bflo(ow.z), bfhi(ow.z), bflo(ow.w), bfhi(ow.w)};
; #pragma unroll
;           for (int j = 0; j < 4; ++j) { o[j] = o[j] * rs * g0[j] * v0[j] * sigmoidf_(v0[j]); o[4 + j] = o[4 + j] * rs * g1[j] * v1[j] * sigmoidf_(v1[j]); }
;           u32x4 w; w.x = pk(o[0], o[1]); w.y = pk(o[2], o[3]); w.z = pk(o[4], o[5]); w.w = pk(o[6], o[7]);
;           gst<u32x4>(op, w);
.LBB0_235:
	v_fma_f32 v138, s26, v138, v204
	v_cmp_gt_f32_e32 vcc, s33, v138
	v_mul_f32_e32 v139, 0x4b800000, v138
	s_nop 0
	v_cndmask_b32_e32 v138, v138, v139, vcc
	v_rsq_f32_e32 v138, v138
	s_nop 0
	v_mul_f32_e32 v139, 0x45800000, v138
	v_cndmask_b32_e32 v148, v138, v139, vcc
	v_mov_b64_e32 v[180:181], v[236:237]
	v_mov_b64_e32 v[136:137], v[242:243]
	v_mov_b64_e32 v[138:139], v[244:245]
	v_mov_b32_e32 v198, v246
	v_lshlrev_b32_e32 v200, 16, v136
	v_pk_mul_f32 v[202:203], v[68:69], v[198:199] op_sel_hi:[1,0]
	v_and_b32_e32 v201, 0xffff0000, v136
	v_mul_f32_e32 v136, 0xbfb8aa3b, v202
	v_exp_f32_e32 v212, v136
	v_mul_f32_e32 v136, 0xbfb8aa3b, v203
	v_exp_f32_e32 v213, v136
	v_pk_mul_f32 v[200:201], v[148:149], v[200:201] op_sel_hi:[0,1]
	v_pk_mul_f32 v[132:133], v[132:133], v[200:201]
	v_pk_add_f32 v[200:201], v[212:213], 1.0 op_sel_hi:[1,0]
	s_nop 0
	v_div_scale_f32 v136, s[26:27], v201, v201, 1.0
	v_rcp_f32_e32 v165, v136
	v_pk_mul_f32 v[132:133], v[202:203], v[132:133]
	v_fma_f32 v167, -v136, v165, 1.0
	v_fmac_f32_e32 v165, v167, v165
	v_div_scale_f32 v167, vcc, 1.0, v201, 1.0
	v_mul_f32_e32 v199, v167, v165
	v_fma_f32 v202, -v136, v199, v167
	v_fmac_f32_e32 v199, v202, v165
	v_fma_f32 v136, -v136, v199, v167
	v_div_fmas_f32 v136, v136, v165, v199
	v_div_fixup_f32 v201, v136, v201, 1.0
	v_div_scale_f32 v136, s[26:27], v200, v200, 1.0
	v_rcp_f32_e32 v165, v136
	s_nop 0
	v_fma_f32 v167, -v136, v165, 1.0
	v_fmac_f32_e32 v165, v167, v165
	v_div_scale_f32 v167, vcc, 1.0, v200, 1.0
	v_mul_f32_e32 v199, v167, v165
	v_fma_f32 v202, -v136, v199, v167
	v_fmac_f32_e32 v199, v202, v165
	v_fma_f32 v136, -v136, v199, v167
	v_div_fmas_f32 v136, v136, v165, v199
	v_pk_mul_f32 v[202:203], v[64:65], v[198:199] op_sel_hi:[1,0]
	v_div_fixup_f32 v200, v136, v200, 1.0
	v_mul_f32_e32 v136, 0xbfb8aa3b, v202
	v_exp_f32_e32 v212, v136
	v_mul_f32_e32 v136, 0xbfb8aa3b, v203
	v_exp_f32_e32 v213, v136
	v_pk_mul_f32 v[132:133], v[200:201], v[132:133]
	v_lshlrev_b32_e32 v200, 16, v138
	v_and_b32_e32 v201, 0xffff0000, v138
	v_pk_mul_f32 v[200:201], v[148:149], v[200:201] op_sel_hi:[0,1]
	v_pk_mul_f32 v[128:129], v[128:129], v[200:201]
	v_pk_add_f32 v[200:201], v[212:213], 1.0 op_sel_hi:[1,0]
	v_pk_mul_f32 v[128:129], v[202:203], v[128:129]
	v_div_scale_f32 v136, s[26:27], v201, v201, 1.0
	v_rcp_f32_e32 v138, v136
	s_nop 0
	v_fma_f32 v165, -v136, v138, 1.0
	v_fmac_f32_e32 v138, v165, v138
	v_div_scale_f32 v165, vcc, 1.0, v201, 1.0
	v_mul_f32_e32 v167, v165, v138
	v_fma_f32 v199, -v136, v167, v165
	v_fmac_f32_e32 v167, v199, v138
	v_fma_f32 v136, -v136, v167, v165
	v_div_fmas_f32 v136, v136, v138, v167
	v_div_fixup_f32 v201, v136, v201, 1.0
	v_div_scale_f32 v136, s[26:27], v200, v200, 1.0
	v_rcp_f32_e32 v138, v136
	s_nop 0
	v_fma_f32 v165, -v136, v138, 1.0
	v_fmac_f32_e32 v138, v165, v138
	v_div_scale_f32 v165, vcc, 1.0, v200, 1.0
	v_mul_f32_e32 v167, v165, v138
	v_fma_f32 v199, -v136, v167, v165
	v_fmac_f32_e32 v167, v199, v138
	v_fma_f32 v136, -v136, v167, v165
	v_div_fmas_f32 v136, v136, v138, v167
	v_div_fixup_f32 v200, v136, v200, 1.0
	v_pk_mul_f32 v[202:203], v[70:71], v[198:199] op_sel_hi:[1,0]
	v_pk_mul_f32 v[128:129], v[200:201], v[128:129]
	v_lshlrev_b32_e32 v200, 16, v137
	v_and_b32_e32 v201, 0xffff0000, v137
	v_mul_f32_e32 v136, 0xbfb8aa3b, v202
	v_mul_f32_e32 v137, 0xbfb8aa3b, v203
	v_exp_f32_e32 v136, v136
	v_exp_f32_e32 v137, v137
	v_pk_mul_f32 v[200:201], v[148:149], v[200:201] op_sel_hi:[0,1]
	v_pk_mul_f32 v[134:135], v[134:135], v[200:201]
	v_pk_add_f32 v[136:137], v[136:137], 1.0 op_sel_hi:[1,0]
	s_nop 0
	v_div_scale_f32 v138, s[26:27], v137, v137, 1.0
	v_rcp_f32_e32 v165, v138
	v_pk_mul_f32 v[134:135], v[202:203], v[134:135]
	v_fma_f32 v167, -v138, v165, 1.0
	v_fmac_f32_e32 v165, v167, v165
	v_div_scale_f32 v167, vcc, 1.0, v137, 1.0
	v_mul_f32_e32 v199, v167, v165
	v_fma_f32 v200, -v138, v199, v167
	v_fmac_f32_e32 v199, v200, v165
	v_fma_f32 v138, -v138, v199, v167
	v_div_fmas_f32 v138, v138, v165, v199
	v_div_fixup_f32 v137, v138, v137, 1.0
	v_div_scale_f32 v138, s[26:27], v136, v136, 1.0
	v_rcp_f32_e32 v165, v138
	s_nop 0
	v_fma_f32 v167, -v138, v165, 1.0
	v_fmac_f32_e32 v165, v167, v165
	v_div_scale_f32 v167, vcc, 1.0, v136, 1.0
	v_mul_f32_e32 v199, v167, v165
	v_fma_f32 v200, -v138, v199, v167
	v_fmac_f32_e32 v199, v200, v165
	v_fma_f32 v138, -v138, v199, v167
	v_div_fmas_f32 v138, v138, v165, v199
	v_div_fixup_f32 v136, v138, v136, 1.0
	v_pk_mul_f32 v[134:135], v[136:137], v[134:135]
	v_lshlrev_b32_e32 v136, 16, v139
	v_and_b32_e32 v137, 0xffff0000, v139
	v_pk_mul_f32 v[138:139], v[66:67], v[198:199] op_sel_hi:[1,0]
	v_pk_mul_f32 v[136:137], v[148:149], v[136:137] op_sel_hi:[0,1]
	v_mul_f32_e32 v165, 0xbfb8aa3b, v138
	v_pk_mul_f32 v[130:131], v[130:131], v[136:137]
	v_mul_f32_e32 v136, 0xbfb8aa3b, v139
	v_exp_f32_e32 v198, v165
	v_exp_f32_e32 v199, v136
	v_pk_mul_f32 v[130:131], v[138:139], v[130:131]
	v_pk_add_f32 v[136:137], v[198:199], 1.0 op_sel_hi:[1,0]
	s_nop 0
	v_div_scale_f32 v138, s[26:27], v137, v137, 1.0
	v_rcp_f32_e32 v139, v138
	s_nop 0
	v_fma_f32 v148, -v138, v139, 1.0
	v_fmac_f32_e32 v139, v148, v139
	v_div_scale_f32 v148, vcc, 1.0, v137, 1.0
	v_mul_f32_e32 v165, v148, v139
	v_fma_f32 v167, -v138, v165, v148
	v_fmac_f32_e32 v165, v167, v139
	v_fma_f32 v138, -v138, v165, v148
	v_div_fmas_f32 v138, v138, v139, v165
	v_div_fixup_f32 v137, v138, v137, 1.0
	v_div_scale_f32 v138, s[26:27], v136, v136, 1.0
	v_rcp_f32_e32 v139, v138
	s_nop 0
	v_fma_f32 v148, -v138, v139, 1.0
	v_fmac_f32_e32 v139, v148, v139
	v_div_scale_f32 v148, vcc, 1.0, v136, 1.0
	v_mul_f32_e32 v165, v148, v139
	v_fma_f32 v167, -v138, v165, v148
	v_fmac_f32_e32 v165, v167, v139
	v_fma_f32 v138, -v138, v165, v148
	v_div_fmas_f32 v138, v138, v139, v165
	v_div_fixup_f32 v136, v138, v136, 1.0
	v_pk_mul_f32 v[136:137], v[136:137], v[130:131]
	v_cvt_pk_bf16_f32 v130, v132, v133
	v_cvt_pk_bf16_f32 v131, v134, v135
	v_cvt_pk_bf16_f32 v132, v128, v129
	v_cvt_pk_bf16_f32 v133, v136, v137
	v_or_b32_e32 v136, 0x80, v164
	s_and_b64 vcc, exec, s[46:47]
	global_store_dwordx4 v[180:181], v[130:133], off
	s_cbranch_vccnz .LBB0_237
	v_readlane_b32 s26, v255, 35
	s_nop 1
	v_and_b32_e32 v148, s26, v136
	v_readlane_b32 s26, v255, 33
	v_readlane_b32 s27, v255, 34
	s_nop 1
	v_lshl_add_u64 v[132:133], v[148:149], 2, s[26:27]
	global_load_dwordx4 v[128:131], v[132:133], off offset:16
	s_nop 0
	global_load_dwordx4 v[132:135], v[132:133], off
	s_branch .LBB0_238
